# conv_item loop hand-rewritten: loads batched, dwconv taps from registers (LDS rows read once), LayerNorm of a wave's 8 rows interleaved
# speedup vs baseline: 1.0194x; 1.0194x over previous
; DI int tidx() { int t = threadIdx.x & 255; asm volatile("" : "+v"(t)); return t; }
; DI float sigm(float x) { return 1.f / (1.f + __expf(-x)); }
; DI void conv_item(PREF p, int l, int tile, unsigned char* ldsb) {
;     ...
;   const int tid = tidx(), lane = tid & 63, w = tid >> 6;
;   const int t0 = tile * 32, s0 = t0 & 4095;
;   __syncthreads();
; #pragma unroll 4
;   for (int id = tid; id < 62 * 32; id += 256) {
;     int rr = id >> 5, ch = (id & 31) * 8;
;     int s = s0 - 30 + rr;
;     float v[8];
; #pragma unroll
;     for (int j = 0; j < 8; ++j) v[j] = 0.f;
;     if (s >= 0) {
;       const u16* src = p.hb + (size_t)(t0 - 30 + rr) * HW + ch;
;       float a[8], g[8];
;       unpack8(*(const u32x4*)(src + OFF_AVAL), a);
;       unpack8(*(const u32x4*)(src + OFF_AGATE), g);
; #pragma unroll
;       for (int j = 0; j < 8; ++j) v[j] = a[j] * sigm(g[j]);
;     }
;     *(float4*)(Gs + rr * 256 + ch) = make_float4(v[0], v[1], v[2], v[3]);
;     *(float4*)(Gs + rr * 256 + ch + 4) = make_float4(v[4], v[5], v[6], v[7]);
;   }
;   __syncthreads();
;   {
;     const int c = tid;
;     float wv[31];
; #pragma unroll
;     for (int j = 0; j < 31; ++j) wv[j] = p.conv_w[((size_t)l * 31 + j) * 256 + c];
;     const float bias = p.conv_b[l * 256 + c];
.LBB0_395:
	v_readfirstlane_b32 s0, v168
	s_lshr_b32 s20, s0, 8
	s_add_i32 s28, s20, s70
	s_cmpk_gt_i32 s28, 0x3ff
	s_mov_b64 s[42:43], 0x12b0100
	s_cbranch_scc1 .LBB0_420
	v_readlane_b32 s0, v254, 46
	v_readlane_b32 s1, v254, 47
	s_load_dwordx8 s[8:15], s[0:1], 0x28
	s_load_dwordx2 s[18:19], s[0:1], 0x140
	s_load_dwordx2 s[20:21], s[0:1], 0x150
	s_mul_i32 s22, s56, 0x7c00
	s_lshl_b32 s23, s56, 10
	s_movk_i32 s17, 0x1540
	v_lshlrev_b32_e32 v79, 2, v169
	v_lshrrev_b32_e32 v100, 5, v169
	v_and_b32_e32 v0, 31, v169
	v_lshlrev_b32_e32 v84, 4, v0
	v_lshlrev_b32_e32 v0, 5, v0
	v_lshl_add_u32 v80, v100, 10, v0
	v_add_u32_e32 v80, s33, v80
	v_add_u32_e32 v81, s33, v79
	v_lshrrev_b32_e32 v0, 6, v169
	v_lshlrev_b32_e32 v0, 13, v0
	v_lshl_add_u32 v82, v172, 4, v0
	v_add_u32_e32 v82, s33, v82
	v_add_u32_e32 v83, -30, v100
	v_xor_b32_e32 v85, 32, v172
	v_xor_b32_e32 v86, 16, v172
	v_xor_b32_e32 v87, 8, v172
	v_xor_b32_e32 v88, 4, v172
	v_xor_b32_e32 v89, 2, v172
	v_xor_b32_e32 v90, 1, v172
	v_lshlrev_b32_e32 v85, 2, v85
	v_lshlrev_b32_e32 v86, 2, v86
	v_lshlrev_b32_e32 v87, 2, v87
	v_lshlrev_b32_e32 v88, 2, v88
	v_lshlrev_b32_e32 v89, 2, v89
	v_lshlrev_b32_e32 v90, 2, v90
	v_lshlrev_b32_e32 v2, 4, v172
	s_waitcnt lgkmcnt(0)
	s_add_u32 s8, s8, s22
	s_addc_u32 s9, s9, 0
	s_add_u32 s10, s10, s23
	s_addc_u32 s11, s11, 0
	s_add_u32 s12, s12, s23
	s_addc_u32 s13, s13, 0
	s_add_u32 s14, s14, s23
	s_addc_u32 s15, s15, 0
	s_add_u32 s24, s8, 0x0
	s_addc_u32 s25, s9, 0
	global_load_dword v117, v79, s[24:25]
	global_load_dword v118, v79, s[24:25] offset:1024
	global_load_dword v119, v79, s[24:25] offset:2048
	global_load_dword v120, v79, s[24:25] offset:3072
	s_add_u32 s24, s8, 0x1000
	s_addc_u32 s25, s9, 0
	global_load_dword v121, v79, s[24:25]
	global_load_dword v122, v79, s[24:25] offset:1024
	global_load_dword v123, v79, s[24:25] offset:2048
	global_load_dword v124, v79, s[24:25] offset:3072
	s_add_u32 s24, s8, 0x2000
	s_addc_u32 s25, s9, 0
	global_load_dword v125, v79, s[24:25]
	global_load_dword v126, v79, s[24:25] offset:1024
	global_load_dword v127, v79, s[24:25] offset:2048
	global_load_dword v128, v79, s[24:25] offset:3072
	s_add_u32 s24, s8, 0x3000
	s_addc_u32 s25, s9, 0
	global_load_dword v129, v79, s[24:25]
	global_load_dword v130, v79, s[24:25] offset:1024
	global_load_dword v131, v79, s[24:25] offset:2048
	global_load_dword v132, v79, s[24:25] offset:3072
	s_add_u32 s24, s8, 0x4000
	s_addc_u32 s25, s9, 0
	global_load_dword v133, v79, s[24:25]
	global_load_dword v134, v79, s[24:25] offset:1024
	global_load_dword v135, v79, s[24:25] offset:2048
	global_load_dword v136, v79, s[24:25] offset:3072
	s_add_u32 s24, s8, 0x5000
	s_addc_u32 s25, s9, 0
	global_load_dword v137, v79, s[24:25]
	global_load_dword v138, v79, s[24:25] offset:1024
	global_load_dword v139, v79, s[24:25] offset:2048
	global_load_dword v140, v79, s[24:25] offset:3072
	s_add_u32 s24, s8, 0x6000
	s_addc_u32 s25, s9, 0
	global_load_dword v141, v79, s[24:25]
	global_load_dword v142, v79, s[24:25] offset:1024
	global_load_dword v143, v79, s[24:25] offset:2048
	global_load_dword v144, v79, s[24:25] offset:3072
	s_add_u32 s24, s8, 0x7000
	s_addc_u32 s25, s9, 0
	global_load_dword v145, v79, s[24:25]
	global_load_dword v146, v79, s[24:25] offset:1024
	global_load_dword v147, v79, s[24:25] offset:2048
	global_load_dword v91, v79, s[10:11]
	global_load_dwordx4 v[92:95], v2, s[12:13]
	global_load_dwordx4 v[96:99], v2, s[14:15]
	v_mov_b32_e32 v104, s18
	v_mov_b32_e32 v105, s19
	v_mov_b32_e32 v4, v84
	v_mov_b32_e32 v5, 0
	v_lshl_add_u64 v[104:105], v[104:105], 0, v[4:5]
.Lmy_conv_item:
	s_lshl_b32 s22, s28, 5
	s_and_b32 s23, s22, 0xfff
	v_add_u32_e32 v106, s22, v83
	v_mov_b32_e32 v0, v106
	v_mad_i64_i32 v[34:35], s[0:1], v0, s17, v[104:105]
	v_add_u32_e32 v0, 8, v106
	v_mad_i64_i32 v[36:37], s[0:1], v0, s17, v[104:105]
	v_add_u32_e32 v0, 16, v106
	v_mad_i64_i32 v[38:39], s[0:1], v0, s17, v[104:105]
	v_add_u32_e32 v0, 24, v106
	v_mad_i64_i32 v[40:41], s[0:1], v0, s17, v[104:105]
	v_add_u32_e32 v0, 32, v106
	v_mad_i64_i32 v[42:43], s[0:1], v0, s17, v[104:105]
	v_add_u32_e32 v0, 40, v106
	v_mad_i64_i32 v[44:45], s[0:1], v0, s17, v[104:105]
	v_add_u32_e32 v0, 48, v106
	v_mad_i64_i32 v[46:47], s[0:1], v0, s17, v[104:105]
	s_add_i32 s26, s22, 31
	v_add_u32_e32 v0, 56, v106
	v_min_i32_e32 v0, s26, v0
	v_mad_i64_i32 v[48:49], s[0:1], v0, s17, v[104:105]
	s_waitcnt lgkmcnt(0)
	s_barrier
; DI float sigm(float x) { return 1.f / (1.f + __expf(-x)); }
; DI void conv_item(PREF p, int l, int tile, unsigned char* ldsb) {
;     ...
; #pragma unroll 4
;   for (int id = tid; id < 62 * 32; id += 256) {
;     int rr = id >> 5, ch = (id & 31) * 8;
;     int s = s0 - 30 + rr;
;     float v[8];
; #pragma unroll
;     for (int j = 0; j < 8; ++j) v[j] = 0.f;
;     if (s >= 0) {
;       const u16* src = p.hb + (size_t)(t0 - 30 + rr) * HW + ch;
;       float a[8], g[8];
;       unpack8(*(const u32x4*)(src + OFF_AVAL), a);
;       unpack8(*(const u32x4*)(src + OFF_AGATE), g);
; #pragma unroll
;       for (int j = 0; j < 8; ++j) v[j] = a[j] * sigm(g[j]);
;     }
;     *(float4*)(Gs + rr * 256 + ch) = make_float4(v[0], v[1], v[2], v[3]);
;     *(float4*)(Gs + rr * 256 + ch + 4) = make_float4(v[4], v[5], v[6], v[7]);
;   }
	global_load_dwordx4 v[182:185], v[34:35], off
	global_load_dwordx4 v[186:189], v[34:35], off offset:512
	global_load_dwordx4 v[190:193], v[36:37], off
	global_load_dwordx4 v[194:197], v[36:37], off offset:512
	global_load_dwordx4 v[198:201], v[38:39], off
	global_load_dwordx4 v[202:205], v[38:39], off offset:512
	global_load_dwordx4 v[206:209], v[40:41], off
	global_load_dwordx4 v[210:213], v[40:41], off offset:512
	global_load_dwordx4 v[214:217], v[42:43], off
	global_load_dwordx4 v[218:221], v[42:43], off offset:512
	global_load_dwordx4 v[222:225], v[44:45], off
	global_load_dwordx4 v[226:229], v[44:45], off offset:512
	global_load_dwordx4 v[230:233], v[46:47], off
	global_load_dwordx4 v[234:237], v[46:47], off offset:512
	global_load_dwordx4 v[238:241], v[48:49], off
	global_load_dwordx4 v[242:245], v[48:49], off offset:512
	s_cmp_eq_u32 s23, 0
	s_cselect_b32 s27, 30, 0
	s_waitcnt vmcnt(14)
	v_lshlrev_b32_e32 v10, 16, v186
	v_and_b32_e32 v11, 0xffff0000, v186
	v_lshlrev_b32_e32 v12, 16, v187
	v_and_b32_e32 v13, 0xffff0000, v187
	v_lshlrev_b32_e32 v14, 16, v188
	v_and_b32_e32 v15, 0xffff0000, v188
	v_lshlrev_b32_e32 v16, 16, v189
	v_and_b32_e32 v17, 0xffff0000, v189
	v_mul_f32_e32 v10, 0xbfb8aa3b, v10
	v_mul_f32_e32 v11, 0xbfb8aa3b, v11
	v_mul_f32_e32 v12, 0xbfb8aa3b, v12
	v_mul_f32_e32 v13, 0xbfb8aa3b, v13
	v_mul_f32_e32 v14, 0xbfb8aa3b, v14
	v_mul_f32_e32 v15, 0xbfb8aa3b, v15
	v_mul_f32_e32 v16, 0xbfb8aa3b, v16
	v_mul_f32_e32 v17, 0xbfb8aa3b, v17
	v_exp_f32_e32 v10, v10
	v_exp_f32_e32 v11, v11
	v_exp_f32_e32 v12, v12
	v_exp_f32_e32 v13, v13
	v_exp_f32_e32 v14, v14
	v_exp_f32_e32 v15, v15
	v_exp_f32_e32 v16, v16
	v_exp_f32_e32 v17, v17
	v_lshlrev_b32_e32 v2, 16, v182
	v_and_b32_e32 v3, 0xffff0000, v182
	v_lshlrev_b32_e32 v4, 16, v183
	v_and_b32_e32 v5, 0xffff0000, v183
	v_lshlrev_b32_e32 v6, 16, v184
	v_and_b32_e32 v7, 0xffff0000, v184
	v_lshlrev_b32_e32 v8, 16, v185
	v_and_b32_e32 v9, 0xffff0000, v185
	v_add_f32_e32 v10, 1.0, v10
	v_add_f32_e32 v11, 1.0, v11
	v_add_f32_e32 v12, 1.0, v12
	v_add_f32_e32 v13, 1.0, v13
	v_add_f32_e32 v14, 1.0, v14
	v_add_f32_e32 v15, 1.0, v15
	v_add_f32_e32 v16, 1.0, v16
	v_add_f32_e32 v17, 1.0, v17
	v_rcp_f32_e32 v10, v10
	v_rcp_f32_e32 v11, v11
	v_rcp_f32_e32 v12, v12
	v_rcp_f32_e32 v13, v13
	v_rcp_f32_e32 v14, v14
	v_rcp_f32_e32 v15, v15
	v_rcp_f32_e32 v16, v16
	v_rcp_f32_e32 v17, v17
	v_add_u32_e32 v0, 0, v100
	v_cmp_le_u32_e32 vcc, s27, v0
	v_mul_f32_e32 v2, v2, v10
	v_mul_f32_e32 v3, v3, v11
	v_mul_f32_e32 v4, v4, v12
	v_mul_f32_e32 v5, v5, v13
	v_mul_f32_e32 v6, v6, v14
	v_mul_f32_e32 v7, v7, v15
	v_mul_f32_e32 v8, v8, v16
	v_mul_f32_e32 v9, v9, v17
	v_cndmask_b32_e32 v2, 0, v2, vcc
	v_cndmask_b32_e32 v3, 0, v3, vcc
	v_cndmask_b32_e32 v4, 0, v4, vcc
	v_cndmask_b32_e32 v5, 0, v5, vcc
	v_cndmask_b32_e32 v6, 0, v6, vcc
	v_cndmask_b32_e32 v7, 0, v7, vcc
	v_cndmask_b32_e32 v8, 0, v8, vcc
	v_cndmask_b32_e32 v9, 0, v9, vcc
	ds_write_b128 v80, v[2:5] offset:0
	ds_write_b128 v80, v[6:9] offset:16
	s_waitcnt vmcnt(12)
	v_lshlrev_b32_e32 v26, 16, v194
	v_and_b32_e32 v27, 0xffff0000, v194
	v_lshlrev_b32_e32 v28, 16, v195
	v_and_b32_e32 v29, 0xffff0000, v195
	v_lshlrev_b32_e32 v30, 16, v196
	v_and_b32_e32 v31, 0xffff0000, v196
	v_lshlrev_b32_e32 v32, 16, v197
	v_and_b32_e32 v33, 0xffff0000, v197
	v_mul_f32_e32 v26, 0xbfb8aa3b, v26
	v_mul_f32_e32 v27, 0xbfb8aa3b, v27
	v_mul_f32_e32 v28, 0xbfb8aa3b, v28
	v_mul_f32_e32 v29, 0xbfb8aa3b, v29
	v_mul_f32_e32 v30, 0xbfb8aa3b, v30
	v_mul_f32_e32 v31, 0xbfb8aa3b, v31
	v_mul_f32_e32 v32, 0xbfb8aa3b, v32
	v_mul_f32_e32 v33, 0xbfb8aa3b, v33
	v_exp_f32_e32 v26, v26
	v_exp_f32_e32 v27, v27
	v_exp_f32_e32 v28, v28
	v_exp_f32_e32 v29, v29
	v_exp_f32_e32 v30, v30
	v_exp_f32_e32 v31, v31
	v_exp_f32_e32 v32, v32
	v_exp_f32_e32 v33, v33
	v_lshlrev_b32_e32 v18, 16, v190
	v_and_b32_e32 v19, 0xffff0000, v190
	v_lshlrev_b32_e32 v20, 16, v191
	v_and_b32_e32 v21, 0xffff0000, v191
	v_lshlrev_b32_e32 v22, 16, v192
	v_and_b32_e32 v23, 0xffff0000, v192
	v_lshlrev_b32_e32 v24, 16, v193
	v_and_b32_e32 v25, 0xffff0000, v193
	v_add_f32_e32 v26, 1.0, v26
	v_add_f32_e32 v27, 1.0, v27
	v_add_f32_e32 v28, 1.0, v28
	v_add_f32_e32 v29, 1.0, v29
	v_add_f32_e32 v30, 1.0, v30
	v_add_f32_e32 v31, 1.0, v31
	v_add_f32_e32 v32, 1.0, v32
	v_add_f32_e32 v33, 1.0, v33
	v_rcp_f32_e32 v26, v26
	v_rcp_f32_e32 v27, v27
	v_rcp_f32_e32 v28, v28
	v_rcp_f32_e32 v29, v29
	v_rcp_f32_e32 v30, v30
	v_rcp_f32_e32 v31, v31
	v_rcp_f32_e32 v32, v32
	v_rcp_f32_e32 v33, v33
	v_add_u32_e32 v0, 8, v100
	v_cmp_le_u32_e32 vcc, s27, v0
	v_mul_f32_e32 v18, v18, v26
	v_mul_f32_e32 v19, v19, v27
	v_mul_f32_e32 v20, v20, v28
	v_mul_f32_e32 v21, v21, v29
	v_mul_f32_e32 v22, v22, v30
	v_mul_f32_e32 v23, v23, v31
	v_mul_f32_e32 v24, v24, v32
	v_mul_f32_e32 v25, v25, v33
	v_cndmask_b32_e32 v18, 0, v18, vcc
	v_cndmask_b32_e32 v19, 0, v19, vcc
	v_cndmask_b32_e32 v20, 0, v20, vcc
	v_cndmask_b32_e32 v21, 0, v21, vcc
	v_cndmask_b32_e32 v22, 0, v22, vcc
	v_cndmask_b32_e32 v23, 0, v23, vcc
	v_cndmask_b32_e32 v24, 0, v24, vcc
	v_cndmask_b32_e32 v25, 0, v25, vcc
	ds_write_b128 v80, v[18:21] offset:8192
	ds_write_b128 v80, v[22:25] offset:8208
	s_waitcnt vmcnt(10)
; DI float sigm(float x) { return 1.f / (1.f + __expf(-x)); }
; DI void conv_item(PREF p, int l, int tile, unsigned char* ldsb) {
;     ...
;   for (int id = tid; id < 62 * 32; id += 256) {
;     int rr = id >> 5, ch = (id & 31) * 8;
;     int s = s0 - 30 + rr;
;     float v[8];
; #pragma unroll
;     for (int j = 0; j < 8; ++j) v[j] = 0.f;
;     if (s >= 0) {
;       const u16* src = p.hb + (size_t)(t0 - 30 + rr) * HW + ch;
;       float a[8], g[8];
;       unpack8(*(const u32x4*)(src + OFF_AVAL), a);
;       unpack8(*(const u32x4*)(src + OFF_AGATE), g);
; #pragma unroll
;       for (int j = 0; j < 8; ++j) v[j] = a[j] * sigm(g[j]);
;     }
;     *(float4*)(Gs + rr * 256 + ch) = make_float4(v[0], v[1], v[2], v[3]);
;     *(float4*)(Gs + rr * 256 + ch + 4) = make_float4(v[4], v[5], v[6], v[7]);
;   }
	v_lshlrev_b32_e32 v10, 16, v202
	v_and_b32_e32 v11, 0xffff0000, v202
	v_lshlrev_b32_e32 v12, 16, v203
	v_and_b32_e32 v13, 0xffff0000, v203
	v_lshlrev_b32_e32 v14, 16, v204
	v_and_b32_e32 v15, 0xffff0000, v204
	v_lshlrev_b32_e32 v16, 16, v205
	v_and_b32_e32 v17, 0xffff0000, v205
	v_mul_f32_e32 v10, 0xbfb8aa3b, v10
	v_mul_f32_e32 v11, 0xbfb8aa3b, v11
	v_mul_f32_e32 v12, 0xbfb8aa3b, v12
	v_mul_f32_e32 v13, 0xbfb8aa3b, v13
	v_mul_f32_e32 v14, 0xbfb8aa3b, v14
	v_mul_f32_e32 v15, 0xbfb8aa3b, v15
	v_mul_f32_e32 v16, 0xbfb8aa3b, v16
	v_mul_f32_e32 v17, 0xbfb8aa3b, v17
	v_exp_f32_e32 v10, v10
	v_exp_f32_e32 v11, v11
	v_exp_f32_e32 v12, v12
	v_exp_f32_e32 v13, v13
	v_exp_f32_e32 v14, v14
	v_exp_f32_e32 v15, v15
	v_exp_f32_e32 v16, v16
	v_exp_f32_e32 v17, v17
	v_lshlrev_b32_e32 v2, 16, v198
	v_and_b32_e32 v3, 0xffff0000, v198
	v_lshlrev_b32_e32 v4, 16, v199
	v_and_b32_e32 v5, 0xffff0000, v199
	v_lshlrev_b32_e32 v6, 16, v200
	v_and_b32_e32 v7, 0xffff0000, v200
	v_lshlrev_b32_e32 v8, 16, v201
	v_and_b32_e32 v9, 0xffff0000, v201
	v_add_f32_e32 v10, 1.0, v10
	v_add_f32_e32 v11, 1.0, v11
	v_add_f32_e32 v12, 1.0, v12
	v_add_f32_e32 v13, 1.0, v13
	v_add_f32_e32 v14, 1.0, v14
	v_add_f32_e32 v15, 1.0, v15
	v_add_f32_e32 v16, 1.0, v16
	v_add_f32_e32 v17, 1.0, v17
	v_rcp_f32_e32 v10, v10
	v_rcp_f32_e32 v11, v11
	v_rcp_f32_e32 v12, v12
	v_rcp_f32_e32 v13, v13
	v_rcp_f32_e32 v14, v14
	v_rcp_f32_e32 v15, v15
	v_rcp_f32_e32 v16, v16
	v_rcp_f32_e32 v17, v17
	v_add_u32_e32 v0, 16, v100
	v_cmp_le_u32_e32 vcc, s27, v0
	v_mul_f32_e32 v2, v2, v10
	v_mul_f32_e32 v3, v3, v11
	v_mul_f32_e32 v4, v4, v12
	v_mul_f32_e32 v5, v5, v13
	v_mul_f32_e32 v6, v6, v14
	v_mul_f32_e32 v7, v7, v15
	v_mul_f32_e32 v8, v8, v16
	v_mul_f32_e32 v9, v9, v17
	v_cndmask_b32_e32 v2, 0, v2, vcc
	v_cndmask_b32_e32 v3, 0, v3, vcc
	v_cndmask_b32_e32 v4, 0, v4, vcc
	v_cndmask_b32_e32 v5, 0, v5, vcc
	v_cndmask_b32_e32 v6, 0, v6, vcc
	v_cndmask_b32_e32 v7, 0, v7, vcc
	v_cndmask_b32_e32 v8, 0, v8, vcc
	v_cndmask_b32_e32 v9, 0, v9, vcc
	ds_write_b128 v80, v[2:5] offset:16384
	ds_write_b128 v80, v[6:9] offset:16400
	s_waitcnt vmcnt(8)
	v_lshlrev_b32_e32 v26, 16, v210
	v_and_b32_e32 v27, 0xffff0000, v210
	v_lshlrev_b32_e32 v28, 16, v211
	v_and_b32_e32 v29, 0xffff0000, v211
	v_lshlrev_b32_e32 v30, 16, v212
	v_and_b32_e32 v31, 0xffff0000, v212
	v_lshlrev_b32_e32 v32, 16, v213
	v_and_b32_e32 v33, 0xffff0000, v213
	v_mul_f32_e32 v26, 0xbfb8aa3b, v26
	v_mul_f32_e32 v27, 0xbfb8aa3b, v27
	v_mul_f32_e32 v28, 0xbfb8aa3b, v28
	v_mul_f32_e32 v29, 0xbfb8aa3b, v29
	v_mul_f32_e32 v30, 0xbfb8aa3b, v30
	v_mul_f32_e32 v31, 0xbfb8aa3b, v31
	v_mul_f32_e32 v32, 0xbfb8aa3b, v32
	v_mul_f32_e32 v33, 0xbfb8aa3b, v33
	v_exp_f32_e32 v26, v26
	v_exp_f32_e32 v27, v27
	v_exp_f32_e32 v28, v28
	v_exp_f32_e32 v29, v29
	v_exp_f32_e32 v30, v30
	v_exp_f32_e32 v31, v31
	v_exp_f32_e32 v32, v32
	v_exp_f32_e32 v33, v33
	v_lshlrev_b32_e32 v18, 16, v206
	v_and_b32_e32 v19, 0xffff0000, v206
	v_lshlrev_b32_e32 v20, 16, v207
	v_and_b32_e32 v21, 0xffff0000, v207
	v_lshlrev_b32_e32 v22, 16, v208
	v_and_b32_e32 v23, 0xffff0000, v208
	v_lshlrev_b32_e32 v24, 16, v209
	v_and_b32_e32 v25, 0xffff0000, v209
	v_add_f32_e32 v26, 1.0, v26
	v_add_f32_e32 v27, 1.0, v27
	v_add_f32_e32 v28, 1.0, v28
	v_add_f32_e32 v29, 1.0, v29
	v_add_f32_e32 v30, 1.0, v30
	v_add_f32_e32 v31, 1.0, v31
	v_add_f32_e32 v32, 1.0, v32
	v_add_f32_e32 v33, 1.0, v33
	v_rcp_f32_e32 v26, v26
	v_rcp_f32_e32 v27, v27
	v_rcp_f32_e32 v28, v28
	v_rcp_f32_e32 v29, v29
	v_rcp_f32_e32 v30, v30
	v_rcp_f32_e32 v31, v31
	v_rcp_f32_e32 v32, v32
	v_rcp_f32_e32 v33, v33
	v_add_u32_e32 v0, 24, v100
	v_cmp_le_u32_e32 vcc, s27, v0
	v_mul_f32_e32 v18, v18, v26
	v_mul_f32_e32 v19, v19, v27
	v_mul_f32_e32 v20, v20, v28
	v_mul_f32_e32 v21, v21, v29
	v_mul_f32_e32 v22, v22, v30
	v_mul_f32_e32 v23, v23, v31
	v_mul_f32_e32 v24, v24, v32
	v_mul_f32_e32 v25, v25, v33
	v_cndmask_b32_e32 v18, 0, v18, vcc
	v_cndmask_b32_e32 v19, 0, v19, vcc
	v_cndmask_b32_e32 v20, 0, v20, vcc
	v_cndmask_b32_e32 v21, 0, v21, vcc
	v_cndmask_b32_e32 v22, 0, v22, vcc
	v_cndmask_b32_e32 v23, 0, v23, vcc
	v_cndmask_b32_e32 v24, 0, v24, vcc
	v_cndmask_b32_e32 v25, 0, v25, vcc
	ds_write_b128 v80, v[18:21] offset:24576
	ds_write_b128 v80, v[22:25] offset:24592
	s_waitcnt vmcnt(6)
	v_lshlrev_b32_e32 v10, 16, v218
	v_and_b32_e32 v11, 0xffff0000, v218
	v_lshlrev_b32_e32 v12, 16, v219
	v_and_b32_e32 v13, 0xffff0000, v219
	v_lshlrev_b32_e32 v14, 16, v220
	v_and_b32_e32 v15, 0xffff0000, v220
	v_lshlrev_b32_e32 v16, 16, v221
	v_and_b32_e32 v17, 0xffff0000, v221
	v_mul_f32_e32 v10, 0xbfb8aa3b, v10
	v_mul_f32_e32 v11, 0xbfb8aa3b, v11
	v_mul_f32_e32 v12, 0xbfb8aa3b, v12
	v_mul_f32_e32 v13, 0xbfb8aa3b, v13
	v_mul_f32_e32 v14, 0xbfb8aa3b, v14
	v_mul_f32_e32 v15, 0xbfb8aa3b, v15
	v_mul_f32_e32 v16, 0xbfb8aa3b, v16
	v_mul_f32_e32 v17, 0xbfb8aa3b, v17
	v_exp_f32_e32 v10, v10
	v_exp_f32_e32 v11, v11
	v_exp_f32_e32 v12, v12
	v_exp_f32_e32 v13, v13
	v_exp_f32_e32 v14, v14
	v_exp_f32_e32 v15, v15
	v_exp_f32_e32 v16, v16
	v_exp_f32_e32 v17, v17
	v_lshlrev_b32_e32 v2, 16, v214
	v_and_b32_e32 v3, 0xffff0000, v214
	v_lshlrev_b32_e32 v4, 16, v215
	v_and_b32_e32 v5, 0xffff0000, v215
	v_lshlrev_b32_e32 v6, 16, v216
	v_and_b32_e32 v7, 0xffff0000, v216
	v_lshlrev_b32_e32 v8, 16, v217
	v_and_b32_e32 v9, 0xffff0000, v217
	v_add_f32_e32 v10, 1.0, v10
	v_add_f32_e32 v11, 1.0, v11
	v_add_f32_e32 v12, 1.0, v12
	v_add_f32_e32 v13, 1.0, v13
	v_add_f32_e32 v14, 1.0, v14
	v_add_f32_e32 v15, 1.0, v15
	v_add_f32_e32 v16, 1.0, v16
	v_add_f32_e32 v17, 1.0, v17
	v_rcp_f32_e32 v10, v10
	v_rcp_f32_e32 v11, v11
	v_rcp_f32_e32 v12, v12
	v_rcp_f32_e32 v13, v13
	v_rcp_f32_e32 v14, v14
	v_rcp_f32_e32 v15, v15
	v_rcp_f32_e32 v16, v16
	v_rcp_f32_e32 v17, v17
	v_add_u32_e32 v0, 32, v100
	v_cmp_le_u32_e32 vcc, s27, v0
	v_mul_f32_e32 v2, v2, v10
	v_mul_f32_e32 v3, v3, v11
	v_mul_f32_e32 v4, v4, v12
	v_mul_f32_e32 v5, v5, v13
	v_mul_f32_e32 v6, v6, v14
	v_mul_f32_e32 v7, v7, v15
	v_mul_f32_e32 v8, v8, v16
	v_mul_f32_e32 v9, v9, v17
	v_cndmask_b32_e32 v2, 0, v2, vcc
	v_cndmask_b32_e32 v3, 0, v3, vcc
	v_cndmask_b32_e32 v4, 0, v4, vcc
	v_cndmask_b32_e32 v5, 0, v5, vcc
	v_cndmask_b32_e32 v6, 0, v6, vcc
	v_cndmask_b32_e32 v7, 0, v7, vcc
	v_cndmask_b32_e32 v8, 0, v8, vcc
	v_cndmask_b32_e32 v9, 0, v9, vcc
	ds_write_b128 v80, v[2:5] offset:32768
	ds_write_b128 v80, v[6:9] offset:32784
	s_waitcnt vmcnt(4)
; DI float sigm(float x) { return 1.f / (1.f + __expf(-x)); }
; DI void conv_item(PREF p, int l, int tile, unsigned char* ldsb) {
;     ...
;   for (int id = tid; id < 62 * 32; id += 256) {
;     int rr = id >> 5, ch = (id & 31) * 8;
;     int s = s0 - 30 + rr;
;     float v[8];
; #pragma unroll
;     for (int j = 0; j < 8; ++j) v[j] = 0.f;
;     if (s >= 0) {
;       const u16* src = p.hb + (size_t)(t0 - 30 + rr) * HW + ch;
;       float a[8], g[8];
;       unpack8(*(const u32x4*)(src + OFF_AVAL), a);
;       unpack8(*(const u32x4*)(src + OFF_AGATE), g);
; #pragma unroll
;       for (int j = 0; j < 8; ++j) v[j] = a[j] * sigm(g[j]);
;     }
;     *(float4*)(Gs + rr * 256 + ch) = make_float4(v[0], v[1], v[2], v[3]);
;     *(float4*)(Gs + rr * 256 + ch + 4) = make_float4(v[4], v[5], v[6], v[7]);
;   }
	v_lshlrev_b32_e32 v26, 16, v226
	v_and_b32_e32 v27, 0xffff0000, v226
	v_lshlrev_b32_e32 v28, 16, v227
	v_and_b32_e32 v29, 0xffff0000, v227
	v_lshlrev_b32_e32 v30, 16, v228
	v_and_b32_e32 v31, 0xffff0000, v228
	v_lshlrev_b32_e32 v32, 16, v229
	v_and_b32_e32 v33, 0xffff0000, v229
	v_mul_f32_e32 v26, 0xbfb8aa3b, v26
	v_mul_f32_e32 v27, 0xbfb8aa3b, v27
	v_mul_f32_e32 v28, 0xbfb8aa3b, v28
	v_mul_f32_e32 v29, 0xbfb8aa3b, v29
	v_mul_f32_e32 v30, 0xbfb8aa3b, v30
	v_mul_f32_e32 v31, 0xbfb8aa3b, v31
	v_mul_f32_e32 v32, 0xbfb8aa3b, v32
	v_mul_f32_e32 v33, 0xbfb8aa3b, v33
	v_exp_f32_e32 v26, v26
	v_exp_f32_e32 v27, v27
	v_exp_f32_e32 v28, v28
	v_exp_f32_e32 v29, v29
	v_exp_f32_e32 v30, v30
	v_exp_f32_e32 v31, v31
	v_exp_f32_e32 v32, v32
	v_exp_f32_e32 v33, v33
	v_lshlrev_b32_e32 v18, 16, v222
	v_and_b32_e32 v19, 0xffff0000, v222
	v_lshlrev_b32_e32 v20, 16, v223
	v_and_b32_e32 v21, 0xffff0000, v223
	v_lshlrev_b32_e32 v22, 16, v224
	v_and_b32_e32 v23, 0xffff0000, v224
	v_lshlrev_b32_e32 v24, 16, v225
	v_and_b32_e32 v25, 0xffff0000, v225
	v_add_f32_e32 v26, 1.0, v26
	v_add_f32_e32 v27, 1.0, v27
	v_add_f32_e32 v28, 1.0, v28
	v_add_f32_e32 v29, 1.0, v29
	v_add_f32_e32 v30, 1.0, v30
	v_add_f32_e32 v31, 1.0, v31
	v_add_f32_e32 v32, 1.0, v32
	v_add_f32_e32 v33, 1.0, v33
	v_rcp_f32_e32 v26, v26
	v_rcp_f32_e32 v27, v27
	v_rcp_f32_e32 v28, v28
	v_rcp_f32_e32 v29, v29
	v_rcp_f32_e32 v30, v30
	v_rcp_f32_e32 v31, v31
	v_rcp_f32_e32 v32, v32
	v_rcp_f32_e32 v33, v33
	v_add_u32_e32 v0, 40, v100
	v_cmp_le_u32_e32 vcc, s27, v0
	v_mul_f32_e32 v18, v18, v26
	v_mul_f32_e32 v19, v19, v27
	v_mul_f32_e32 v20, v20, v28
	v_mul_f32_e32 v21, v21, v29
	v_mul_f32_e32 v22, v22, v30
	v_mul_f32_e32 v23, v23, v31
	v_mul_f32_e32 v24, v24, v32
	v_mul_f32_e32 v25, v25, v33
	v_cndmask_b32_e32 v18, 0, v18, vcc
	v_cndmask_b32_e32 v19, 0, v19, vcc
	v_cndmask_b32_e32 v20, 0, v20, vcc
	v_cndmask_b32_e32 v21, 0, v21, vcc
	v_cndmask_b32_e32 v22, 0, v22, vcc
	v_cndmask_b32_e32 v23, 0, v23, vcc
	v_cndmask_b32_e32 v24, 0, v24, vcc
	v_cndmask_b32_e32 v25, 0, v25, vcc
	ds_write_b128 v80, v[18:21] offset:40960
	ds_write_b128 v80, v[22:25] offset:40976
	s_waitcnt vmcnt(2)
	v_lshlrev_b32_e32 v10, 16, v234
	v_and_b32_e32 v11, 0xffff0000, v234
	v_lshlrev_b32_e32 v12, 16, v235
	v_and_b32_e32 v13, 0xffff0000, v235
	v_lshlrev_b32_e32 v14, 16, v236
	v_and_b32_e32 v15, 0xffff0000, v236
	v_lshlrev_b32_e32 v16, 16, v237
	v_and_b32_e32 v17, 0xffff0000, v237
	v_mul_f32_e32 v10, 0xbfb8aa3b, v10
	v_mul_f32_e32 v11, 0xbfb8aa3b, v11
	v_mul_f32_e32 v12, 0xbfb8aa3b, v12
	v_mul_f32_e32 v13, 0xbfb8aa3b, v13
	v_mul_f32_e32 v14, 0xbfb8aa3b, v14
	v_mul_f32_e32 v15, 0xbfb8aa3b, v15
	v_mul_f32_e32 v16, 0xbfb8aa3b, v16
	v_mul_f32_e32 v17, 0xbfb8aa3b, v17
	v_exp_f32_e32 v10, v10
	v_exp_f32_e32 v11, v11
	v_exp_f32_e32 v12, v12
	v_exp_f32_e32 v13, v13
	v_exp_f32_e32 v14, v14
	v_exp_f32_e32 v15, v15
	v_exp_f32_e32 v16, v16
	v_exp_f32_e32 v17, v17
	v_lshlrev_b32_e32 v2, 16, v230
	v_and_b32_e32 v3, 0xffff0000, v230
	v_lshlrev_b32_e32 v4, 16, v231
	v_and_b32_e32 v5, 0xffff0000, v231
	v_lshlrev_b32_e32 v6, 16, v232
	v_and_b32_e32 v7, 0xffff0000, v232
	v_lshlrev_b32_e32 v8, 16, v233
	v_and_b32_e32 v9, 0xffff0000, v233
	v_add_f32_e32 v10, 1.0, v10
	v_add_f32_e32 v11, 1.0, v11
	v_add_f32_e32 v12, 1.0, v12
	v_add_f32_e32 v13, 1.0, v13
	v_add_f32_e32 v14, 1.0, v14
	v_add_f32_e32 v15, 1.0, v15
	v_add_f32_e32 v16, 1.0, v16
	v_add_f32_e32 v17, 1.0, v17
	v_rcp_f32_e32 v10, v10
	v_rcp_f32_e32 v11, v11
	v_rcp_f32_e32 v12, v12
	v_rcp_f32_e32 v13, v13
	v_rcp_f32_e32 v14, v14
	v_rcp_f32_e32 v15, v15
	v_rcp_f32_e32 v16, v16
	v_rcp_f32_e32 v17, v17
	v_add_u32_e32 v0, 48, v100
	v_cmp_le_u32_e32 vcc, s27, v0
	v_mul_f32_e32 v2, v2, v10
	v_mul_f32_e32 v3, v3, v11
	v_mul_f32_e32 v4, v4, v12
	v_mul_f32_e32 v5, v5, v13
	v_mul_f32_e32 v6, v6, v14
	v_mul_f32_e32 v7, v7, v15
	v_mul_f32_e32 v8, v8, v16
	v_mul_f32_e32 v9, v9, v17
	v_cndmask_b32_e32 v2, 0, v2, vcc
	v_cndmask_b32_e32 v3, 0, v3, vcc
	v_cndmask_b32_e32 v4, 0, v4, vcc
	v_cndmask_b32_e32 v5, 0, v5, vcc
	v_cndmask_b32_e32 v6, 0, v6, vcc
	v_cndmask_b32_e32 v7, 0, v7, vcc
	v_cndmask_b32_e32 v8, 0, v8, vcc
	v_cndmask_b32_e32 v9, 0, v9, vcc
	ds_write_b128 v80, v[2:5] offset:49152
	ds_write_b128 v80, v[6:9] offset:49168
	s_waitcnt vmcnt(0)
	v_lshlrev_b32_e32 v26, 16, v242
	v_and_b32_e32 v27, 0xffff0000, v242
	v_lshlrev_b32_e32 v28, 16, v243
	v_and_b32_e32 v29, 0xffff0000, v243
	v_lshlrev_b32_e32 v30, 16, v244
	v_and_b32_e32 v31, 0xffff0000, v244
	v_lshlrev_b32_e32 v32, 16, v245
	v_and_b32_e32 v33, 0xffff0000, v245
	v_mul_f32_e32 v26, 0xbfb8aa3b, v26
	v_mul_f32_e32 v27, 0xbfb8aa3b, v27
	v_mul_f32_e32 v28, 0xbfb8aa3b, v28
	v_mul_f32_e32 v29, 0xbfb8aa3b, v29
	v_mul_f32_e32 v30, 0xbfb8aa3b, v30
	v_mul_f32_e32 v31, 0xbfb8aa3b, v31
	v_mul_f32_e32 v32, 0xbfb8aa3b, v32
	v_mul_f32_e32 v33, 0xbfb8aa3b, v33
	v_exp_f32_e32 v26, v26
	v_exp_f32_e32 v27, v27
	v_exp_f32_e32 v28, v28
	v_exp_f32_e32 v29, v29
	v_exp_f32_e32 v30, v30
	v_exp_f32_e32 v31, v31
	v_exp_f32_e32 v32, v32
	v_exp_f32_e32 v33, v33
	v_lshlrev_b32_e32 v18, 16, v238
	v_and_b32_e32 v19, 0xffff0000, v238
	v_lshlrev_b32_e32 v20, 16, v239
	v_and_b32_e32 v21, 0xffff0000, v239
	v_lshlrev_b32_e32 v22, 16, v240
	v_and_b32_e32 v23, 0xffff0000, v240
	v_lshlrev_b32_e32 v24, 16, v241
	v_and_b32_e32 v25, 0xffff0000, v241
	v_add_f32_e32 v26, 1.0, v26
	v_add_f32_e32 v27, 1.0, v27
	v_add_f32_e32 v28, 1.0, v28
	v_add_f32_e32 v29, 1.0, v29
	v_add_f32_e32 v30, 1.0, v30
	v_add_f32_e32 v31, 1.0, v31
	v_add_f32_e32 v32, 1.0, v32
	v_add_f32_e32 v33, 1.0, v33
	v_rcp_f32_e32 v26, v26
	v_rcp_f32_e32 v27, v27
	v_rcp_f32_e32 v28, v28
	v_rcp_f32_e32 v29, v29
	v_rcp_f32_e32 v30, v30
	v_rcp_f32_e32 v31, v31
	v_rcp_f32_e32 v32, v32
	v_rcp_f32_e32 v33, v33
	v_add_u32_e32 v0, 56, v100
	v_cmp_le_u32_e32 vcc, s27, v0
	v_mul_f32_e32 v18, v18, v26
	v_mul_f32_e32 v19, v19, v27
	v_mul_f32_e32 v20, v20, v28
	v_mul_f32_e32 v21, v21, v29
	v_mul_f32_e32 v22, v22, v30
	v_mul_f32_e32 v23, v23, v31
	v_mul_f32_e32 v24, v24, v32
	v_mul_f32_e32 v25, v25, v33
	v_cndmask_b32_e32 v18, 0, v18, vcc
	v_cndmask_b32_e32 v19, 0, v19, vcc
	v_cndmask_b32_e32 v20, 0, v20, vcc
	v_cndmask_b32_e32 v21, 0, v21, vcc
	v_cndmask_b32_e32 v22, 0, v22, vcc
	v_cndmask_b32_e32 v23, 0, v23, vcc
	v_cndmask_b32_e32 v24, 0, v24, vcc
	v_cndmask_b32_e32 v25, 0, v25, vcc
	ds_write_b128 v80, v[18:21] offset:57344
	ds_write_b128 v80, v[22:25] offset:57360
	s_waitcnt lgkmcnt(0)
	s_barrier
; DI void conv_item(PREF p, int l, int tile, unsigned char* ldsb) {
;     ...
;   {
;     const int c = tid;
;     float wv[31];
; #pragma unroll
;     for (int j = 0; j < 31; ++j) wv[j] = p.conv_w[((size_t)l * 31 + j) * 256 + c];
;     const float bias = p.conv_b[l * 256 + c];
;     for (int tt = 0; tt < 32; ++tt) {
;       float acc = bias;
; #pragma unroll
;       for (int j = 0; j < 31; ++j) acc += wv[j] * Gs[(tt + j) * 256 + c];
;       Gs[tt * 256 + c] = acc;
;     }
;   }
	ds_read2st64_b32 v[182:183], v81 offset0:0 offset1:4
	ds_read2st64_b32 v[184:185], v81 offset0:8 offset1:12
	ds_read2st64_b32 v[186:187], v81 offset0:16 offset1:20
	ds_read2st64_b32 v[188:189], v81 offset0:24 offset1:28
	ds_read2st64_b32 v[190:191], v81 offset0:32 offset1:36
	ds_read2st64_b32 v[192:193], v81 offset0:40 offset1:44
	ds_read2st64_b32 v[194:195], v81 offset0:48 offset1:52
	ds_read2st64_b32 v[196:197], v81 offset0:56 offset1:60
	ds_read2st64_b32 v[198:199], v81 offset0:64 offset1:68
	ds_read2st64_b32 v[200:201], v81 offset0:72 offset1:76
	ds_read2st64_b32 v[202:203], v81 offset0:80 offset1:84
	ds_read2st64_b32 v[204:205], v81 offset0:88 offset1:92
	ds_read2st64_b32 v[206:207], v81 offset0:96 offset1:100
	ds_read2st64_b32 v[208:209], v81 offset0:104 offset1:108
	ds_read2st64_b32 v[210:211], v81 offset0:112 offset1:116
	ds_read2st64_b32 v[212:213], v81 offset0:120 offset1:124
	ds_read2st64_b32 v[214:215], v81 offset0:128 offset1:132
	ds_read2st64_b32 v[216:217], v81 offset0:136 offset1:140
	ds_read2st64_b32 v[218:219], v81 offset0:144 offset1:148
	ds_read2st64_b32 v[220:221], v81 offset0:152 offset1:156
	ds_read2st64_b32 v[222:223], v81 offset0:160 offset1:164
	ds_read2st64_b32 v[224:225], v81 offset0:168 offset1:172
	ds_read2st64_b32 v[226:227], v81 offset0:176 offset1:180
	ds_read2st64_b32 v[228:229], v81 offset0:184 offset1:188
	ds_read2st64_b32 v[230:231], v81 offset0:192 offset1:196
	ds_read2st64_b32 v[232:233], v81 offset0:200 offset1:204
	ds_read2st64_b32 v[234:235], v81 offset0:208 offset1:212
	ds_read2st64_b32 v[236:237], v81 offset0:216 offset1:220
	ds_read2st64_b32 v[238:239], v81 offset0:224 offset1:228
	ds_read2st64_b32 v[240:241], v81 offset0:232 offset1:236
	ds_read2st64_b32 v[242:243], v81 offset0:240 offset1:244
	s_waitcnt vmcnt(0) lgkmcnt(0)
	v_fma_f32 v2, v117, v182, v91
	v_fma_f32 v3, v117, v183, v91
	v_fma_f32 v4, v117, v184, v91
	v_fma_f32 v5, v117, v185, v91
	v_fmac_f32_e32 v2, v118, v183
	v_fmac_f32_e32 v3, v118, v184
	v_fmac_f32_e32 v4, v118, v185
	v_fmac_f32_e32 v5, v118, v186
	v_fmac_f32_e32 v2, v119, v184
	v_fmac_f32_e32 v3, v119, v185
	v_fmac_f32_e32 v4, v119, v186
	v_fmac_f32_e32 v5, v119, v187
	v_fmac_f32_e32 v2, v120, v185
	v_fmac_f32_e32 v3, v120, v186
	v_fmac_f32_e32 v4, v120, v187
	v_fmac_f32_e32 v5, v120, v188
	v_fmac_f32_e32 v2, v121, v186
	v_fmac_f32_e32 v3, v121, v187
	v_fmac_f32_e32 v4, v121, v188
	v_fmac_f32_e32 v5, v121, v189
	v_fmac_f32_e32 v2, v122, v187
	v_fmac_f32_e32 v3, v122, v188
	v_fmac_f32_e32 v4, v122, v189
	v_fmac_f32_e32 v5, v122, v190
	v_fmac_f32_e32 v2, v123, v188
	v_fmac_f32_e32 v3, v123, v189
	v_fmac_f32_e32 v4, v123, v190
	v_fmac_f32_e32 v5, v123, v191
	v_fmac_f32_e32 v2, v124, v189
	v_fmac_f32_e32 v3, v124, v190
	v_fmac_f32_e32 v4, v124, v191
	v_fmac_f32_e32 v5, v124, v192
	v_fmac_f32_e32 v2, v125, v190
	v_fmac_f32_e32 v3, v125, v191
	v_fmac_f32_e32 v4, v125, v192
	v_fmac_f32_e32 v5, v125, v193
	v_fmac_f32_e32 v2, v126, v191
	v_fmac_f32_e32 v3, v126, v192
	v_fmac_f32_e32 v4, v126, v193
	v_fmac_f32_e32 v5, v126, v194
	v_fmac_f32_e32 v2, v127, v192
	v_fmac_f32_e32 v3, v127, v193
	v_fmac_f32_e32 v4, v127, v194
	v_fmac_f32_e32 v5, v127, v195
	v_fmac_f32_e32 v2, v128, v193
	v_fmac_f32_e32 v3, v128, v194
	v_fmac_f32_e32 v4, v128, v195
	v_fmac_f32_e32 v5, v128, v196
	v_fmac_f32_e32 v2, v129, v194
	v_fmac_f32_e32 v3, v129, v195
	v_fmac_f32_e32 v4, v129, v196
	v_fmac_f32_e32 v5, v129, v197
	v_fmac_f32_e32 v2, v130, v195
	v_fmac_f32_e32 v3, v130, v196
	v_fmac_f32_e32 v4, v130, v197
	v_fmac_f32_e32 v5, v130, v198
	v_fmac_f32_e32 v2, v131, v196
	v_fmac_f32_e32 v3, v131, v197
	v_fmac_f32_e32 v4, v131, v198
	v_fmac_f32_e32 v5, v131, v199
	v_fmac_f32_e32 v2, v132, v197
	v_fmac_f32_e32 v3, v132, v198
	v_fmac_f32_e32 v4, v132, v199
	v_fmac_f32_e32 v5, v132, v200
	v_fmac_f32_e32 v2, v133, v198
	v_fmac_f32_e32 v3, v133, v199
	v_fmac_f32_e32 v4, v133, v200
	v_fmac_f32_e32 v5, v133, v201
	v_fmac_f32_e32 v2, v134, v199
	v_fmac_f32_e32 v3, v134, v200
	v_fmac_f32_e32 v4, v134, v201
	v_fmac_f32_e32 v5, v134, v202
	v_fmac_f32_e32 v2, v135, v200
	v_fmac_f32_e32 v3, v135, v201
	v_fmac_f32_e32 v4, v135, v202
	v_fmac_f32_e32 v5, v135, v203
	v_fmac_f32_e32 v2, v136, v201
	v_fmac_f32_e32 v3, v136, v202
	v_fmac_f32_e32 v4, v136, v203
	v_fmac_f32_e32 v5, v136, v204
	v_fmac_f32_e32 v2, v137, v202
	v_fmac_f32_e32 v3, v137, v203
	v_fmac_f32_e32 v4, v137, v204
	v_fmac_f32_e32 v5, v137, v205
	v_fmac_f32_e32 v2, v138, v203
	v_fmac_f32_e32 v3, v138, v204
	v_fmac_f32_e32 v4, v138, v205
	v_fmac_f32_e32 v5, v138, v206
	v_fmac_f32_e32 v2, v139, v204
	v_fmac_f32_e32 v3, v139, v205
	v_fmac_f32_e32 v4, v139, v206
	v_fmac_f32_e32 v5, v139, v207
	v_fmac_f32_e32 v2, v140, v205
	v_fmac_f32_e32 v3, v140, v206
	v_fmac_f32_e32 v4, v140, v207
	v_fmac_f32_e32 v5, v140, v208
	v_fmac_f32_e32 v2, v141, v206
	v_fmac_f32_e32 v3, v141, v207
	v_fmac_f32_e32 v4, v141, v208
	v_fmac_f32_e32 v5, v141, v209
	v_fmac_f32_e32 v2, v142, v207
	v_fmac_f32_e32 v3, v142, v208
	v_fmac_f32_e32 v4, v142, v209
	v_fmac_f32_e32 v5, v142, v210
	v_fmac_f32_e32 v2, v143, v208
	v_fmac_f32_e32 v3, v143, v209
	v_fmac_f32_e32 v4, v143, v210
	v_fmac_f32_e32 v5, v143, v211
	v_fmac_f32_e32 v2, v144, v209
	v_fmac_f32_e32 v3, v144, v210
	v_fmac_f32_e32 v4, v144, v211
	v_fmac_f32_e32 v5, v144, v212
	v_fmac_f32_e32 v2, v145, v210
	v_fmac_f32_e32 v3, v145, v211
	v_fmac_f32_e32 v4, v145, v212
	v_fmac_f32_e32 v5, v145, v213
	v_fmac_f32_e32 v2, v146, v211
	v_fmac_f32_e32 v3, v146, v212
	v_fmac_f32_e32 v4, v146, v213
	v_fmac_f32_e32 v5, v146, v214
	v_fmac_f32_e32 v2, v147, v212
	v_fmac_f32_e32 v3, v147, v213
	v_fmac_f32_e32 v4, v147, v214
	v_fmac_f32_e32 v5, v147, v215
; DI void conv_item(PREF p, int l, int tile, unsigned char* ldsb) {
;     ...
;   {
;     const int c = tid;
;     float wv[31];
; #pragma unroll
;     for (int j = 0; j < 31; ++j) wv[j] = p.conv_w[((size_t)l * 31 + j) * 256 + c];
;     const float bias = p.conv_b[l * 256 + c];
;     for (int tt = 0; tt < 32; ++tt) {
;       float acc = bias;
; #pragma unroll
;       for (int j = 0; j < 31; ++j) acc += wv[j] * Gs[(tt + j) * 256 + c];
;       Gs[tt * 256 + c] = acc;
;     }
;   }
	ds_write2st64_b32 v81, v2, v3 offset0:0 offset1:4
	ds_write2st64_b32 v81, v4, v5 offset0:8 offset1:12
	v_fma_f32 v6, v117, v186, v91
	v_fma_f32 v7, v117, v187, v91
	v_fma_f32 v8, v117, v188, v91
	v_fma_f32 v9, v117, v189, v91
	v_fmac_f32_e32 v6, v118, v187
	v_fmac_f32_e32 v7, v118, v188
	v_fmac_f32_e32 v8, v118, v189
	v_fmac_f32_e32 v9, v118, v190
	v_fmac_f32_e32 v6, v119, v188
	v_fmac_f32_e32 v7, v119, v189
	v_fmac_f32_e32 v8, v119, v190
	v_fmac_f32_e32 v9, v119, v191
	v_fmac_f32_e32 v6, v120, v189
	v_fmac_f32_e32 v7, v120, v190
	v_fmac_f32_e32 v8, v120, v191
	v_fmac_f32_e32 v9, v120, v192
	v_fmac_f32_e32 v6, v121, v190
	v_fmac_f32_e32 v7, v121, v191
	v_fmac_f32_e32 v8, v121, v192
	v_fmac_f32_e32 v9, v121, v193
	v_fmac_f32_e32 v6, v122, v191
	v_fmac_f32_e32 v7, v122, v192
	v_fmac_f32_e32 v8, v122, v193
	v_fmac_f32_e32 v9, v122, v194
	v_fmac_f32_e32 v6, v123, v192
	v_fmac_f32_e32 v7, v123, v193
	v_fmac_f32_e32 v8, v123, v194
	v_fmac_f32_e32 v9, v123, v195
	v_fmac_f32_e32 v6, v124, v193
	v_fmac_f32_e32 v7, v124, v194
	v_fmac_f32_e32 v8, v124, v195
	v_fmac_f32_e32 v9, v124, v196
	v_fmac_f32_e32 v6, v125, v194
	v_fmac_f32_e32 v7, v125, v195
	v_fmac_f32_e32 v8, v125, v196
	v_fmac_f32_e32 v9, v125, v197
	v_fmac_f32_e32 v6, v126, v195
	v_fmac_f32_e32 v7, v126, v196
	v_fmac_f32_e32 v8, v126, v197
	v_fmac_f32_e32 v9, v126, v198
	v_fmac_f32_e32 v6, v127, v196
	v_fmac_f32_e32 v7, v127, v197
	v_fmac_f32_e32 v8, v127, v198
	v_fmac_f32_e32 v9, v127, v199
	v_fmac_f32_e32 v6, v128, v197
	v_fmac_f32_e32 v7, v128, v198
	v_fmac_f32_e32 v8, v128, v199
	v_fmac_f32_e32 v9, v128, v200
	v_fmac_f32_e32 v6, v129, v198
	v_fmac_f32_e32 v7, v129, v199
	v_fmac_f32_e32 v8, v129, v200
	v_fmac_f32_e32 v9, v129, v201
	v_fmac_f32_e32 v6, v130, v199
	v_fmac_f32_e32 v7, v130, v200
	v_fmac_f32_e32 v8, v130, v201
	v_fmac_f32_e32 v9, v130, v202
	v_fmac_f32_e32 v6, v131, v200
	v_fmac_f32_e32 v7, v131, v201
	v_fmac_f32_e32 v8, v131, v202
	v_fmac_f32_e32 v9, v131, v203
	v_fmac_f32_e32 v6, v132, v201
	v_fmac_f32_e32 v7, v132, v202
	v_fmac_f32_e32 v8, v132, v203
	v_fmac_f32_e32 v9, v132, v204
	v_fmac_f32_e32 v6, v133, v202
	v_fmac_f32_e32 v7, v133, v203
	v_fmac_f32_e32 v8, v133, v204
	v_fmac_f32_e32 v9, v133, v205
	v_fmac_f32_e32 v6, v134, v203
	v_fmac_f32_e32 v7, v134, v204
	v_fmac_f32_e32 v8, v134, v205
	v_fmac_f32_e32 v9, v134, v206
	v_fmac_f32_e32 v6, v135, v204
	v_fmac_f32_e32 v7, v135, v205
	v_fmac_f32_e32 v8, v135, v206
	v_fmac_f32_e32 v9, v135, v207
	v_fmac_f32_e32 v6, v136, v205
	v_fmac_f32_e32 v7, v136, v206
	v_fmac_f32_e32 v8, v136, v207
	v_fmac_f32_e32 v9, v136, v208
	v_fmac_f32_e32 v6, v137, v206
	v_fmac_f32_e32 v7, v137, v207
	v_fmac_f32_e32 v8, v137, v208
	v_fmac_f32_e32 v9, v137, v209
	v_fmac_f32_e32 v6, v138, v207
	v_fmac_f32_e32 v7, v138, v208
	v_fmac_f32_e32 v8, v138, v209
	v_fmac_f32_e32 v9, v138, v210
	v_fmac_f32_e32 v6, v139, v208
	v_fmac_f32_e32 v7, v139, v209
	v_fmac_f32_e32 v8, v139, v210
	v_fmac_f32_e32 v9, v139, v211
	v_fmac_f32_e32 v6, v140, v209
	v_fmac_f32_e32 v7, v140, v210
	v_fmac_f32_e32 v8, v140, v211
	v_fmac_f32_e32 v9, v140, v212
	v_fmac_f32_e32 v6, v141, v210
	v_fmac_f32_e32 v7, v141, v211
	v_fmac_f32_e32 v8, v141, v212
	v_fmac_f32_e32 v9, v141, v213
	v_fmac_f32_e32 v6, v142, v211
	v_fmac_f32_e32 v7, v142, v212
	v_fmac_f32_e32 v8, v142, v213
	v_fmac_f32_e32 v9, v142, v214
	v_fmac_f32_e32 v6, v143, v212
	v_fmac_f32_e32 v7, v143, v213
	v_fmac_f32_e32 v8, v143, v214
	v_fmac_f32_e32 v9, v143, v215
	v_fmac_f32_e32 v6, v144, v213
	v_fmac_f32_e32 v7, v144, v214
	v_fmac_f32_e32 v8, v144, v215
	v_fmac_f32_e32 v9, v144, v216
	v_fmac_f32_e32 v6, v145, v214
	v_fmac_f32_e32 v7, v145, v215
	v_fmac_f32_e32 v8, v145, v216
	v_fmac_f32_e32 v9, v145, v217
	v_fmac_f32_e32 v6, v146, v215
	v_fmac_f32_e32 v7, v146, v216
	v_fmac_f32_e32 v8, v146, v217
	v_fmac_f32_e32 v9, v146, v218
	v_fmac_f32_e32 v6, v147, v216
	v_fmac_f32_e32 v7, v147, v217
	v_fmac_f32_e32 v8, v147, v218
	v_fmac_f32_e32 v9, v147, v219
	ds_write2st64_b32 v81, v6, v7 offset0:16 offset1:20
	ds_write2st64_b32 v81, v8, v9 offset0:24 offset1:28
	v_fma_f32 v2, v117, v190, v91
	v_fma_f32 v3, v117, v191, v91
	v_fma_f32 v4, v117, v192, v91
	v_fma_f32 v5, v117, v193, v91
	v_fmac_f32_e32 v2, v118, v191
	v_fmac_f32_e32 v3, v118, v192
	v_fmac_f32_e32 v4, v118, v193
	v_fmac_f32_e32 v5, v118, v194
	v_fmac_f32_e32 v2, v119, v192
	v_fmac_f32_e32 v3, v119, v193
	v_fmac_f32_e32 v4, v119, v194
	v_fmac_f32_e32 v5, v119, v195
	v_fmac_f32_e32 v2, v120, v193
	v_fmac_f32_e32 v3, v120, v194
	v_fmac_f32_e32 v4, v120, v195
	v_fmac_f32_e32 v5, v120, v196
	v_fmac_f32_e32 v2, v121, v194
	v_fmac_f32_e32 v3, v121, v195
	v_fmac_f32_e32 v4, v121, v196
	v_fmac_f32_e32 v5, v121, v197
	v_fmac_f32_e32 v2, v122, v195
	v_fmac_f32_e32 v3, v122, v196
	v_fmac_f32_e32 v4, v122, v197
	v_fmac_f32_e32 v5, v122, v198
	v_fmac_f32_e32 v2, v123, v196
	v_fmac_f32_e32 v3, v123, v197
	v_fmac_f32_e32 v4, v123, v198
	v_fmac_f32_e32 v5, v123, v199
	v_fmac_f32_e32 v2, v124, v197
	v_fmac_f32_e32 v3, v124, v198
	v_fmac_f32_e32 v4, v124, v199
	v_fmac_f32_e32 v5, v124, v200
	v_fmac_f32_e32 v2, v125, v198
	v_fmac_f32_e32 v3, v125, v199
	v_fmac_f32_e32 v4, v125, v200
	v_fmac_f32_e32 v5, v125, v201
	v_fmac_f32_e32 v2, v126, v199
	v_fmac_f32_e32 v3, v126, v200
	v_fmac_f32_e32 v4, v126, v201
	v_fmac_f32_e32 v5, v126, v202
	v_fmac_f32_e32 v2, v127, v200
	v_fmac_f32_e32 v3, v127, v201
	v_fmac_f32_e32 v4, v127, v202
	v_fmac_f32_e32 v5, v127, v203
	v_fmac_f32_e32 v2, v128, v201
	v_fmac_f32_e32 v3, v128, v202
	v_fmac_f32_e32 v4, v128, v203
	v_fmac_f32_e32 v5, v128, v204
	v_fmac_f32_e32 v2, v129, v202
	v_fmac_f32_e32 v3, v129, v203
	v_fmac_f32_e32 v4, v129, v204
; DI void conv_item(PREF p, int l, int tile, unsigned char* ldsb) {
;     ...
;   {
;     const int c = tid;
;     float wv[31];
; #pragma unroll
;     for (int j = 0; j < 31; ++j) wv[j] = p.conv_w[((size_t)l * 31 + j) * 256 + c];
;     const float bias = p.conv_b[l * 256 + c];
;     for (int tt = 0; tt < 32; ++tt) {
;       float acc = bias;
; #pragma unroll
;       for (int j = 0; j < 31; ++j) acc += wv[j] * Gs[(tt + j) * 256 + c];
;       Gs[tt * 256 + c] = acc;
;     }
;   }
	v_fmac_f32_e32 v5, v129, v205
	v_fmac_f32_e32 v2, v130, v203
	v_fmac_f32_e32 v3, v130, v204
	v_fmac_f32_e32 v4, v130, v205
	v_fmac_f32_e32 v5, v130, v206
	v_fmac_f32_e32 v2, v131, v204
	v_fmac_f32_e32 v3, v131, v205
	v_fmac_f32_e32 v4, v131, v206
	v_fmac_f32_e32 v5, v131, v207
	v_fmac_f32_e32 v2, v132, v205
	v_fmac_f32_e32 v3, v132, v206
	v_fmac_f32_e32 v4, v132, v207
	v_fmac_f32_e32 v5, v132, v208
	v_fmac_f32_e32 v2, v133, v206
	v_fmac_f32_e32 v3, v133, v207
	v_fmac_f32_e32 v4, v133, v208
	v_fmac_f32_e32 v5, v133, v209
	v_fmac_f32_e32 v2, v134, v207
	v_fmac_f32_e32 v3, v134, v208
	v_fmac_f32_e32 v4, v134, v209
	v_fmac_f32_e32 v5, v134, v210
	v_fmac_f32_e32 v2, v135, v208
	v_fmac_f32_e32 v3, v135, v209
	v_fmac_f32_e32 v4, v135, v210
	v_fmac_f32_e32 v5, v135, v211
	v_fmac_f32_e32 v2, v136, v209
	v_fmac_f32_e32 v3, v136, v210
	v_fmac_f32_e32 v4, v136, v211
	v_fmac_f32_e32 v5, v136, v212
	v_fmac_f32_e32 v2, v137, v210
	v_fmac_f32_e32 v3, v137, v211
	v_fmac_f32_e32 v4, v137, v212
	v_fmac_f32_e32 v5, v137, v213
	v_fmac_f32_e32 v2, v138, v211
	v_fmac_f32_e32 v3, v138, v212
	v_fmac_f32_e32 v4, v138, v213
	v_fmac_f32_e32 v5, v138, v214
	v_fmac_f32_e32 v2, v139, v212
	v_fmac_f32_e32 v3, v139, v213
	v_fmac_f32_e32 v4, v139, v214
	v_fmac_f32_e32 v5, v139, v215
	v_fmac_f32_e32 v2, v140, v213
	v_fmac_f32_e32 v3, v140, v214
	v_fmac_f32_e32 v4, v140, v215
	v_fmac_f32_e32 v5, v140, v216
	v_fmac_f32_e32 v2, v141, v214
	v_fmac_f32_e32 v3, v141, v215
	v_fmac_f32_e32 v4, v141, v216
	v_fmac_f32_e32 v5, v141, v217
	v_fmac_f32_e32 v2, v142, v215
	v_fmac_f32_e32 v3, v142, v216
	v_fmac_f32_e32 v4, v142, v217
	v_fmac_f32_e32 v5, v142, v218
	v_fmac_f32_e32 v2, v143, v216
	v_fmac_f32_e32 v3, v143, v217
	v_fmac_f32_e32 v4, v143, v218
	v_fmac_f32_e32 v5, v143, v219
	v_fmac_f32_e32 v2, v144, v217
	v_fmac_f32_e32 v3, v144, v218
	v_fmac_f32_e32 v4, v144, v219
	v_fmac_f32_e32 v5, v144, v220
	v_fmac_f32_e32 v2, v145, v218
	v_fmac_f32_e32 v3, v145, v219
	v_fmac_f32_e32 v4, v145, v220
	v_fmac_f32_e32 v5, v145, v221
	v_fmac_f32_e32 v2, v146, v219
	v_fmac_f32_e32 v3, v146, v220
	v_fmac_f32_e32 v4, v146, v221
	v_fmac_f32_e32 v5, v146, v222
	v_fmac_f32_e32 v2, v147, v220
	v_fmac_f32_e32 v3, v147, v221
	v_fmac_f32_e32 v4, v147, v222
	v_fmac_f32_e32 v5, v147, v223
	ds_write2st64_b32 v81, v2, v3 offset0:32 offset1:36
	ds_write2st64_b32 v81, v4, v5 offset0:40 offset1:44
	v_fma_f32 v6, v117, v194, v91
	v_fma_f32 v7, v117, v195, v91
	v_fma_f32 v8, v117, v196, v91
	v_fma_f32 v9, v117, v197, v91
	v_fmac_f32_e32 v6, v118, v195
	v_fmac_f32_e32 v7, v118, v196
	v_fmac_f32_e32 v8, v118, v197
	v_fmac_f32_e32 v9, v118, v198
	v_fmac_f32_e32 v6, v119, v196
	v_fmac_f32_e32 v7, v119, v197
	v_fmac_f32_e32 v8, v119, v198
	v_fmac_f32_e32 v9, v119, v199
	v_fmac_f32_e32 v6, v120, v197
	v_fmac_f32_e32 v7, v120, v198
	v_fmac_f32_e32 v8, v120, v199
	v_fmac_f32_e32 v9, v120, v200
	v_fmac_f32_e32 v6, v121, v198
	v_fmac_f32_e32 v7, v121, v199
	v_fmac_f32_e32 v8, v121, v200
	v_fmac_f32_e32 v9, v121, v201
	v_fmac_f32_e32 v6, v122, v199
	v_fmac_f32_e32 v7, v122, v200
	v_fmac_f32_e32 v8, v122, v201
	v_fmac_f32_e32 v9, v122, v202
	v_fmac_f32_e32 v6, v123, v200
	v_fmac_f32_e32 v7, v123, v201
	v_fmac_f32_e32 v8, v123, v202
	v_fmac_f32_e32 v9, v123, v203
	v_fmac_f32_e32 v6, v124, v201
	v_fmac_f32_e32 v7, v124, v202
	v_fmac_f32_e32 v8, v124, v203
	v_fmac_f32_e32 v9, v124, v204
	v_fmac_f32_e32 v6, v125, v202
	v_fmac_f32_e32 v7, v125, v203
	v_fmac_f32_e32 v8, v125, v204
	v_fmac_f32_e32 v9, v125, v205
	v_fmac_f32_e32 v6, v126, v203
	v_fmac_f32_e32 v7, v126, v204
	v_fmac_f32_e32 v8, v126, v205
	v_fmac_f32_e32 v9, v126, v206
	v_fmac_f32_e32 v6, v127, v204
	v_fmac_f32_e32 v7, v127, v205
	v_fmac_f32_e32 v8, v127, v206
	v_fmac_f32_e32 v9, v127, v207
	v_fmac_f32_e32 v6, v128, v205
	v_fmac_f32_e32 v7, v128, v206
	v_fmac_f32_e32 v8, v128, v207
	v_fmac_f32_e32 v9, v128, v208
	v_fmac_f32_e32 v6, v129, v206
	v_fmac_f32_e32 v7, v129, v207
	v_fmac_f32_e32 v8, v129, v208
	v_fmac_f32_e32 v9, v129, v209
	v_fmac_f32_e32 v6, v130, v207
	v_fmac_f32_e32 v7, v130, v208
	v_fmac_f32_e32 v8, v130, v209
	v_fmac_f32_e32 v9, v130, v210
	v_fmac_f32_e32 v6, v131, v208
	v_fmac_f32_e32 v7, v131, v209
	v_fmac_f32_e32 v8, v131, v210
	v_fmac_f32_e32 v9, v131, v211
	v_fmac_f32_e32 v6, v132, v209
	v_fmac_f32_e32 v7, v132, v210
	v_fmac_f32_e32 v8, v132, v211
	v_fmac_f32_e32 v9, v132, v212
	v_fmac_f32_e32 v6, v133, v210
	v_fmac_f32_e32 v7, v133, v211
	v_fmac_f32_e32 v8, v133, v212
	v_fmac_f32_e32 v9, v133, v213
	v_fmac_f32_e32 v6, v134, v211
	v_fmac_f32_e32 v7, v134, v212
	v_fmac_f32_e32 v8, v134, v213
	v_fmac_f32_e32 v9, v134, v214
	v_fmac_f32_e32 v6, v135, v212
	v_fmac_f32_e32 v7, v135, v213
	v_fmac_f32_e32 v8, v135, v214
	v_fmac_f32_e32 v9, v135, v215
	v_fmac_f32_e32 v6, v136, v213
	v_fmac_f32_e32 v7, v136, v214
	v_fmac_f32_e32 v8, v136, v215
	v_fmac_f32_e32 v9, v136, v216
	v_fmac_f32_e32 v6, v137, v214
	v_fmac_f32_e32 v7, v137, v215
	v_fmac_f32_e32 v8, v137, v216
	v_fmac_f32_e32 v9, v137, v217
	v_fmac_f32_e32 v6, v138, v215
	v_fmac_f32_e32 v7, v138, v216
	v_fmac_f32_e32 v8, v138, v217
	v_fmac_f32_e32 v9, v138, v218
	v_fmac_f32_e32 v6, v139, v216
	v_fmac_f32_e32 v7, v139, v217
	v_fmac_f32_e32 v8, v139, v218
	v_fmac_f32_e32 v9, v139, v219
	v_fmac_f32_e32 v6, v140, v217
	v_fmac_f32_e32 v7, v140, v218
	v_fmac_f32_e32 v8, v140, v219
	v_fmac_f32_e32 v9, v140, v220
	v_fmac_f32_e32 v6, v141, v218
	v_fmac_f32_e32 v7, v141, v219
	v_fmac_f32_e32 v8, v141, v220
	v_fmac_f32_e32 v9, v141, v221
	v_fmac_f32_e32 v6, v142, v219
	v_fmac_f32_e32 v7, v142, v220
	v_fmac_f32_e32 v8, v142, v221
	v_fmac_f32_e32 v9, v142, v222
	v_fmac_f32_e32 v6, v143, v220
	v_fmac_f32_e32 v7, v143, v221
; DI void conv_item(PREF p, int l, int tile, unsigned char* ldsb) {
;     ...
;   {
;     const int c = tid;
;     float wv[31];
; #pragma unroll
;     for (int j = 0; j < 31; ++j) wv[j] = p.conv_w[((size_t)l * 31 + j) * 256 + c];
;     const float bias = p.conv_b[l * 256 + c];
;     for (int tt = 0; tt < 32; ++tt) {
;       float acc = bias;
; #pragma unroll
;       for (int j = 0; j < 31; ++j) acc += wv[j] * Gs[(tt + j) * 256 + c];
;       Gs[tt * 256 + c] = acc;
;     }
;   }
	v_fmac_f32_e32 v8, v143, v222
	v_fmac_f32_e32 v9, v143, v223
	v_fmac_f32_e32 v6, v144, v221
	v_fmac_f32_e32 v7, v144, v222
	v_fmac_f32_e32 v8, v144, v223
	v_fmac_f32_e32 v9, v144, v224
	v_fmac_f32_e32 v6, v145, v222
	v_fmac_f32_e32 v7, v145, v223
	v_fmac_f32_e32 v8, v145, v224
	v_fmac_f32_e32 v9, v145, v225
	v_fmac_f32_e32 v6, v146, v223
	v_fmac_f32_e32 v7, v146, v224
	v_fmac_f32_e32 v8, v146, v225
	v_fmac_f32_e32 v9, v146, v226
	v_fmac_f32_e32 v6, v147, v224
	v_fmac_f32_e32 v7, v147, v225
	v_fmac_f32_e32 v8, v147, v226
	v_fmac_f32_e32 v9, v147, v227
	ds_write2st64_b32 v81, v6, v7 offset0:48 offset1:52
	ds_write2st64_b32 v81, v8, v9 offset0:56 offset1:60
	v_fma_f32 v2, v117, v198, v91
	v_fma_f32 v3, v117, v199, v91
	v_fma_f32 v4, v117, v200, v91
	v_fma_f32 v5, v117, v201, v91
	v_fmac_f32_e32 v2, v118, v199
	v_fmac_f32_e32 v3, v118, v200
	v_fmac_f32_e32 v4, v118, v201
	v_fmac_f32_e32 v5, v118, v202
	v_fmac_f32_e32 v2, v119, v200
	v_fmac_f32_e32 v3, v119, v201
	v_fmac_f32_e32 v4, v119, v202
	v_fmac_f32_e32 v5, v119, v203
	v_fmac_f32_e32 v2, v120, v201
	v_fmac_f32_e32 v3, v120, v202
	v_fmac_f32_e32 v4, v120, v203
	v_fmac_f32_e32 v5, v120, v204
	v_fmac_f32_e32 v2, v121, v202
	v_fmac_f32_e32 v3, v121, v203
	v_fmac_f32_e32 v4, v121, v204
	v_fmac_f32_e32 v5, v121, v205
	v_fmac_f32_e32 v2, v122, v203
	v_fmac_f32_e32 v3, v122, v204
	v_fmac_f32_e32 v4, v122, v205
	v_fmac_f32_e32 v5, v122, v206
	v_fmac_f32_e32 v2, v123, v204
	v_fmac_f32_e32 v3, v123, v205
	v_fmac_f32_e32 v4, v123, v206
	v_fmac_f32_e32 v5, v123, v207
	v_fmac_f32_e32 v2, v124, v205
	v_fmac_f32_e32 v3, v124, v206
	v_fmac_f32_e32 v4, v124, v207
	v_fmac_f32_e32 v5, v124, v208
	v_fmac_f32_e32 v2, v125, v206
	v_fmac_f32_e32 v3, v125, v207
	v_fmac_f32_e32 v4, v125, v208
	v_fmac_f32_e32 v5, v125, v209
	v_fmac_f32_e32 v2, v126, v207
	v_fmac_f32_e32 v3, v126, v208
	v_fmac_f32_e32 v4, v126, v209
	v_fmac_f32_e32 v5, v126, v210
	v_fmac_f32_e32 v2, v127, v208
	v_fmac_f32_e32 v3, v127, v209
	v_fmac_f32_e32 v4, v127, v210
	v_fmac_f32_e32 v5, v127, v211
	v_fmac_f32_e32 v2, v128, v209
	v_fmac_f32_e32 v3, v128, v210
	v_fmac_f32_e32 v4, v128, v211
	v_fmac_f32_e32 v5, v128, v212
	v_fmac_f32_e32 v2, v129, v210
	v_fmac_f32_e32 v3, v129, v211
	v_fmac_f32_e32 v4, v129, v212
	v_fmac_f32_e32 v5, v129, v213
	v_fmac_f32_e32 v2, v130, v211
	v_fmac_f32_e32 v3, v130, v212
	v_fmac_f32_e32 v4, v130, v213
	v_fmac_f32_e32 v5, v130, v214
	v_fmac_f32_e32 v2, v131, v212
	v_fmac_f32_e32 v3, v131, v213
	v_fmac_f32_e32 v4, v131, v214
	v_fmac_f32_e32 v5, v131, v215
	v_fmac_f32_e32 v2, v132, v213
	v_fmac_f32_e32 v3, v132, v214
	v_fmac_f32_e32 v4, v132, v215
	v_fmac_f32_e32 v5, v132, v216
	v_fmac_f32_e32 v2, v133, v214
	v_fmac_f32_e32 v3, v133, v215
	v_fmac_f32_e32 v4, v133, v216
	v_fmac_f32_e32 v5, v133, v217
	v_fmac_f32_e32 v2, v134, v215
	v_fmac_f32_e32 v3, v134, v216
	v_fmac_f32_e32 v4, v134, v217
	v_fmac_f32_e32 v5, v134, v218
	v_fmac_f32_e32 v2, v135, v216
	v_fmac_f32_e32 v3, v135, v217
	v_fmac_f32_e32 v4, v135, v218
	v_fmac_f32_e32 v5, v135, v219
	v_fmac_f32_e32 v2, v136, v217
	v_fmac_f32_e32 v3, v136, v218
	v_fmac_f32_e32 v4, v136, v219
	v_fmac_f32_e32 v5, v136, v220
	v_fmac_f32_e32 v2, v137, v218
	v_fmac_f32_e32 v3, v137, v219
	v_fmac_f32_e32 v4, v137, v220
	v_fmac_f32_e32 v5, v137, v221
	v_fmac_f32_e32 v2, v138, v219
	v_fmac_f32_e32 v3, v138, v220
	v_fmac_f32_e32 v4, v138, v221
	v_fmac_f32_e32 v5, v138, v222
	v_fmac_f32_e32 v2, v139, v220
	v_fmac_f32_e32 v3, v139, v221
	v_fmac_f32_e32 v4, v139, v222
	v_fmac_f32_e32 v5, v139, v223
	v_fmac_f32_e32 v2, v140, v221
	v_fmac_f32_e32 v3, v140, v222
	v_fmac_f32_e32 v4, v140, v223
	v_fmac_f32_e32 v5, v140, v224
	v_fmac_f32_e32 v2, v141, v222
	v_fmac_f32_e32 v3, v141, v223
	v_fmac_f32_e32 v4, v141, v224
	v_fmac_f32_e32 v5, v141, v225
	v_fmac_f32_e32 v2, v142, v223
	v_fmac_f32_e32 v3, v142, v224
	v_fmac_f32_e32 v4, v142, v225
	v_fmac_f32_e32 v5, v142, v226
	v_fmac_f32_e32 v2, v143, v224
	v_fmac_f32_e32 v3, v143, v225
	v_fmac_f32_e32 v4, v143, v226
	v_fmac_f32_e32 v5, v143, v227
	v_fmac_f32_e32 v2, v144, v225
	v_fmac_f32_e32 v3, v144, v226
	v_fmac_f32_e32 v4, v144, v227
	v_fmac_f32_e32 v5, v144, v228
	v_fmac_f32_e32 v2, v145, v226
	v_fmac_f32_e32 v3, v145, v227
	v_fmac_f32_e32 v4, v145, v228
	v_fmac_f32_e32 v5, v145, v229
	v_fmac_f32_e32 v2, v146, v227
	v_fmac_f32_e32 v3, v146, v228
	v_fmac_f32_e32 v4, v146, v229
	v_fmac_f32_e32 v5, v146, v230
	v_fmac_f32_e32 v2, v147, v228
	v_fmac_f32_e32 v3, v147, v229
	v_fmac_f32_e32 v4, v147, v230
	v_fmac_f32_e32 v5, v147, v231
	ds_write2st64_b32 v81, v2, v3 offset0:64 offset1:68
	ds_write2st64_b32 v81, v4, v5 offset0:72 offset1:76
	v_fma_f32 v6, v117, v202, v91
	v_fma_f32 v7, v117, v203, v91
	v_fma_f32 v8, v117, v204, v91
	v_fma_f32 v9, v117, v205, v91
	v_fmac_f32_e32 v6, v118, v203
	v_fmac_f32_e32 v7, v118, v204
	v_fmac_f32_e32 v8, v118, v205
	v_fmac_f32_e32 v9, v118, v206
	v_fmac_f32_e32 v6, v119, v204
	v_fmac_f32_e32 v7, v119, v205
	v_fmac_f32_e32 v8, v119, v206
	v_fmac_f32_e32 v9, v119, v207
	v_fmac_f32_e32 v6, v120, v205
	v_fmac_f32_e32 v7, v120, v206
	v_fmac_f32_e32 v8, v120, v207
	v_fmac_f32_e32 v9, v120, v208
	v_fmac_f32_e32 v6, v121, v206
	v_fmac_f32_e32 v7, v121, v207
	v_fmac_f32_e32 v8, v121, v208
	v_fmac_f32_e32 v9, v121, v209
	v_fmac_f32_e32 v6, v122, v207
	v_fmac_f32_e32 v7, v122, v208
	v_fmac_f32_e32 v8, v122, v209
	v_fmac_f32_e32 v9, v122, v210
	v_fmac_f32_e32 v6, v123, v208
	v_fmac_f32_e32 v7, v123, v209
	v_fmac_f32_e32 v8, v123, v210
	v_fmac_f32_e32 v9, v123, v211
	v_fmac_f32_e32 v6, v124, v209
	v_fmac_f32_e32 v7, v124, v210
	v_fmac_f32_e32 v8, v124, v211
	v_fmac_f32_e32 v9, v124, v212
	v_fmac_f32_e32 v6, v125, v210
; DI void conv_item(PREF p, int l, int tile, unsigned char* ldsb) {
;     ...
;   {
;     const int c = tid;
;     float wv[31];
; #pragma unroll
;     for (int j = 0; j < 31; ++j) wv[j] = p.conv_w[((size_t)l * 31 + j) * 256 + c];
;     const float bias = p.conv_b[l * 256 + c];
;     for (int tt = 0; tt < 32; ++tt) {
;       float acc = bias;
; #pragma unroll
;       for (int j = 0; j < 31; ++j) acc += wv[j] * Gs[(tt + j) * 256 + c];
;       Gs[tt * 256 + c] = acc;
;     }
;   }
	v_fmac_f32_e32 v7, v125, v211
	v_fmac_f32_e32 v8, v125, v212
	v_fmac_f32_e32 v9, v125, v213
	v_fmac_f32_e32 v6, v126, v211
	v_fmac_f32_e32 v7, v126, v212
	v_fmac_f32_e32 v8, v126, v213
	v_fmac_f32_e32 v9, v126, v214
	v_fmac_f32_e32 v6, v127, v212
	v_fmac_f32_e32 v7, v127, v213
	v_fmac_f32_e32 v8, v127, v214
	v_fmac_f32_e32 v9, v127, v215
	v_fmac_f32_e32 v6, v128, v213
	v_fmac_f32_e32 v7, v128, v214
	v_fmac_f32_e32 v8, v128, v215
	v_fmac_f32_e32 v9, v128, v216
	v_fmac_f32_e32 v6, v129, v214
	v_fmac_f32_e32 v7, v129, v215
	v_fmac_f32_e32 v8, v129, v216
	v_fmac_f32_e32 v9, v129, v217
	v_fmac_f32_e32 v6, v130, v215
	v_fmac_f32_e32 v7, v130, v216
	v_fmac_f32_e32 v8, v130, v217
	v_fmac_f32_e32 v9, v130, v218
	v_fmac_f32_e32 v6, v131, v216
	v_fmac_f32_e32 v7, v131, v217
	v_fmac_f32_e32 v8, v131, v218
	v_fmac_f32_e32 v9, v131, v219
	v_fmac_f32_e32 v6, v132, v217
	v_fmac_f32_e32 v7, v132, v218
	v_fmac_f32_e32 v8, v132, v219
	v_fmac_f32_e32 v9, v132, v220
	v_fmac_f32_e32 v6, v133, v218
	v_fmac_f32_e32 v7, v133, v219
	v_fmac_f32_e32 v8, v133, v220
	v_fmac_f32_e32 v9, v133, v221
	v_fmac_f32_e32 v6, v134, v219
	v_fmac_f32_e32 v7, v134, v220
	v_fmac_f32_e32 v8, v134, v221
	v_fmac_f32_e32 v9, v134, v222
	v_fmac_f32_e32 v6, v135, v220
	v_fmac_f32_e32 v7, v135, v221
	v_fmac_f32_e32 v8, v135, v222
	v_fmac_f32_e32 v9, v135, v223
	v_fmac_f32_e32 v6, v136, v221
	v_fmac_f32_e32 v7, v136, v222
	v_fmac_f32_e32 v8, v136, v223
	v_fmac_f32_e32 v9, v136, v224
	v_fmac_f32_e32 v6, v137, v222
	v_fmac_f32_e32 v7, v137, v223
	v_fmac_f32_e32 v8, v137, v224
	v_fmac_f32_e32 v9, v137, v225
	v_fmac_f32_e32 v6, v138, v223
	v_fmac_f32_e32 v7, v138, v224
	v_fmac_f32_e32 v8, v138, v225
	v_fmac_f32_e32 v9, v138, v226
	v_fmac_f32_e32 v6, v139, v224
	v_fmac_f32_e32 v7, v139, v225
	v_fmac_f32_e32 v8, v139, v226
	v_fmac_f32_e32 v9, v139, v227
	v_fmac_f32_e32 v6, v140, v225
	v_fmac_f32_e32 v7, v140, v226
	v_fmac_f32_e32 v8, v140, v227
	v_fmac_f32_e32 v9, v140, v228
	v_fmac_f32_e32 v6, v141, v226
	v_fmac_f32_e32 v7, v141, v227
	v_fmac_f32_e32 v8, v141, v228
	v_fmac_f32_e32 v9, v141, v229
	v_fmac_f32_e32 v6, v142, v227
	v_fmac_f32_e32 v7, v142, v228
	v_fmac_f32_e32 v8, v142, v229
	v_fmac_f32_e32 v9, v142, v230
	v_fmac_f32_e32 v6, v143, v228
	v_fmac_f32_e32 v7, v143, v229
	v_fmac_f32_e32 v8, v143, v230
	v_fmac_f32_e32 v9, v143, v231
	v_fmac_f32_e32 v6, v144, v229
	v_fmac_f32_e32 v7, v144, v230
	v_fmac_f32_e32 v8, v144, v231
	v_fmac_f32_e32 v9, v144, v232
	v_fmac_f32_e32 v6, v145, v230
	v_fmac_f32_e32 v7, v145, v231
	v_fmac_f32_e32 v8, v145, v232
	v_fmac_f32_e32 v9, v145, v233
	v_fmac_f32_e32 v6, v146, v231
	v_fmac_f32_e32 v7, v146, v232
	v_fmac_f32_e32 v8, v146, v233
	v_fmac_f32_e32 v9, v146, v234
	v_fmac_f32_e32 v6, v147, v232
	v_fmac_f32_e32 v7, v147, v233
	v_fmac_f32_e32 v8, v147, v234
	v_fmac_f32_e32 v9, v147, v235
	ds_write2st64_b32 v81, v6, v7 offset0:80 offset1:84
	ds_write2st64_b32 v81, v8, v9 offset0:88 offset1:92
	v_fma_f32 v2, v117, v206, v91
	v_fma_f32 v3, v117, v207, v91
	v_fma_f32 v4, v117, v208, v91
	v_fma_f32 v5, v117, v209, v91
	v_fmac_f32_e32 v2, v118, v207
	v_fmac_f32_e32 v3, v118, v208
	v_fmac_f32_e32 v4, v118, v209
	v_fmac_f32_e32 v5, v118, v210
	v_fmac_f32_e32 v2, v119, v208
	v_fmac_f32_e32 v3, v119, v209
	v_fmac_f32_e32 v4, v119, v210
	v_fmac_f32_e32 v5, v119, v211
	v_fmac_f32_e32 v2, v120, v209
	v_fmac_f32_e32 v3, v120, v210
	v_fmac_f32_e32 v4, v120, v211
	v_fmac_f32_e32 v5, v120, v212
	v_fmac_f32_e32 v2, v121, v210
	v_fmac_f32_e32 v3, v121, v211
	v_fmac_f32_e32 v4, v121, v212
	v_fmac_f32_e32 v5, v121, v213
	v_fmac_f32_e32 v2, v122, v211
	v_fmac_f32_e32 v3, v122, v212
	v_fmac_f32_e32 v4, v122, v213
	v_fmac_f32_e32 v5, v122, v214
	v_fmac_f32_e32 v2, v123, v212
	v_fmac_f32_e32 v3, v123, v213
	v_fmac_f32_e32 v4, v123, v214
	v_fmac_f32_e32 v5, v123, v215
	v_fmac_f32_e32 v2, v124, v213
	v_fmac_f32_e32 v3, v124, v214
	v_fmac_f32_e32 v4, v124, v215
	v_fmac_f32_e32 v5, v124, v216
	v_fmac_f32_e32 v2, v125, v214
	v_fmac_f32_e32 v3, v125, v215
	v_fmac_f32_e32 v4, v125, v216
	v_fmac_f32_e32 v5, v125, v217
	v_fmac_f32_e32 v2, v126, v215
	v_fmac_f32_e32 v3, v126, v216
	v_fmac_f32_e32 v4, v126, v217
	v_fmac_f32_e32 v5, v126, v218
	v_fmac_f32_e32 v2, v127, v216
	v_fmac_f32_e32 v3, v127, v217
	v_fmac_f32_e32 v4, v127, v218
	v_fmac_f32_e32 v5, v127, v219
	v_fmac_f32_e32 v2, v128, v217
	v_fmac_f32_e32 v3, v128, v218
	v_fmac_f32_e32 v4, v128, v219
	v_fmac_f32_e32 v5, v128, v220
	v_fmac_f32_e32 v2, v129, v218
	v_fmac_f32_e32 v3, v129, v219
	v_fmac_f32_e32 v4, v129, v220
	v_fmac_f32_e32 v5, v129, v221
	v_fmac_f32_e32 v2, v130, v219
	v_fmac_f32_e32 v3, v130, v220
	v_fmac_f32_e32 v4, v130, v221
	v_fmac_f32_e32 v5, v130, v222
	v_fmac_f32_e32 v2, v131, v220
	v_fmac_f32_e32 v3, v131, v221
	v_fmac_f32_e32 v4, v131, v222
	v_fmac_f32_e32 v5, v131, v223
	v_fmac_f32_e32 v2, v132, v221
	v_fmac_f32_e32 v3, v132, v222
	v_fmac_f32_e32 v4, v132, v223
	v_fmac_f32_e32 v5, v132, v224
	v_fmac_f32_e32 v2, v133, v222
	v_fmac_f32_e32 v3, v133, v223
	v_fmac_f32_e32 v4, v133, v224
	v_fmac_f32_e32 v5, v133, v225
	v_fmac_f32_e32 v2, v134, v223
	v_fmac_f32_e32 v3, v134, v224
	v_fmac_f32_e32 v4, v134, v225
	v_fmac_f32_e32 v5, v134, v226
	v_fmac_f32_e32 v2, v135, v224
	v_fmac_f32_e32 v3, v135, v225
	v_fmac_f32_e32 v4, v135, v226
	v_fmac_f32_e32 v5, v135, v227
	v_fmac_f32_e32 v2, v136, v225
	v_fmac_f32_e32 v3, v136, v226
	v_fmac_f32_e32 v4, v136, v227
	v_fmac_f32_e32 v5, v136, v228
	v_fmac_f32_e32 v2, v137, v226
	v_fmac_f32_e32 v3, v137, v227
	v_fmac_f32_e32 v4, v137, v228
	v_fmac_f32_e32 v5, v137, v229
	v_fmac_f32_e32 v2, v138, v227
	v_fmac_f32_e32 v3, v138, v228
	v_fmac_f32_e32 v4, v138, v229
	v_fmac_f32_e32 v5, v138, v230
; DI void conv_item(PREF p, int l, int tile, unsigned char* ldsb) {
;     ...
;   {
;     const int c = tid;
;     float wv[31];
; #pragma unroll
;     for (int j = 0; j < 31; ++j) wv[j] = p.conv_w[((size_t)l * 31 + j) * 256 + c];
;     const float bias = p.conv_b[l * 256 + c];
;     for (int tt = 0; tt < 32; ++tt) {
;       float acc = bias;
; #pragma unroll
;       for (int j = 0; j < 31; ++j) acc += wv[j] * Gs[(tt + j) * 256 + c];
;       Gs[tt * 256 + c] = acc;
;     }
;   }
	v_fmac_f32_e32 v2, v139, v228
	v_fmac_f32_e32 v3, v139, v229
	v_fmac_f32_e32 v4, v139, v230
	v_fmac_f32_e32 v5, v139, v231
	v_fmac_f32_e32 v2, v140, v229
	v_fmac_f32_e32 v3, v140, v230
	v_fmac_f32_e32 v4, v140, v231
	v_fmac_f32_e32 v5, v140, v232
	v_fmac_f32_e32 v2, v141, v230
	v_fmac_f32_e32 v3, v141, v231
	v_fmac_f32_e32 v4, v141, v232
	v_fmac_f32_e32 v5, v141, v233
	v_fmac_f32_e32 v2, v142, v231
	v_fmac_f32_e32 v3, v142, v232
	v_fmac_f32_e32 v4, v142, v233
	v_fmac_f32_e32 v5, v142, v234
	v_fmac_f32_e32 v2, v143, v232
	v_fmac_f32_e32 v3, v143, v233
	v_fmac_f32_e32 v4, v143, v234
	v_fmac_f32_e32 v5, v143, v235
	v_fmac_f32_e32 v2, v144, v233
	v_fmac_f32_e32 v3, v144, v234
	v_fmac_f32_e32 v4, v144, v235
	v_fmac_f32_e32 v5, v144, v236
	v_fmac_f32_e32 v2, v145, v234
	v_fmac_f32_e32 v3, v145, v235
	v_fmac_f32_e32 v4, v145, v236
	v_fmac_f32_e32 v5, v145, v237
	v_fmac_f32_e32 v2, v146, v235
	v_fmac_f32_e32 v3, v146, v236
	v_fmac_f32_e32 v4, v146, v237
	v_fmac_f32_e32 v5, v146, v238
	v_fmac_f32_e32 v2, v147, v236
	v_fmac_f32_e32 v3, v147, v237
	v_fmac_f32_e32 v4, v147, v238
	v_fmac_f32_e32 v5, v147, v239
	ds_write2st64_b32 v81, v2, v3 offset0:96 offset1:100
	ds_write2st64_b32 v81, v4, v5 offset0:104 offset1:108
	v_fma_f32 v6, v117, v210, v91
	v_fma_f32 v7, v117, v211, v91
	v_fma_f32 v8, v117, v212, v91
	v_fma_f32 v9, v117, v213, v91
	v_fmac_f32_e32 v6, v118, v211
	v_fmac_f32_e32 v7, v118, v212
	v_fmac_f32_e32 v8, v118, v213
	v_fmac_f32_e32 v9, v118, v214
	v_fmac_f32_e32 v6, v119, v212
	v_fmac_f32_e32 v7, v119, v213
	v_fmac_f32_e32 v8, v119, v214
	v_fmac_f32_e32 v9, v119, v215
	v_fmac_f32_e32 v6, v120, v213
	v_fmac_f32_e32 v7, v120, v214
	v_fmac_f32_e32 v8, v120, v215
	v_fmac_f32_e32 v9, v120, v216
	v_fmac_f32_e32 v6, v121, v214
	v_fmac_f32_e32 v7, v121, v215
	v_fmac_f32_e32 v8, v121, v216
	v_fmac_f32_e32 v9, v121, v217
	v_fmac_f32_e32 v6, v122, v215
	v_fmac_f32_e32 v7, v122, v216
	v_fmac_f32_e32 v8, v122, v217
	v_fmac_f32_e32 v9, v122, v218
	v_fmac_f32_e32 v6, v123, v216
	v_fmac_f32_e32 v7, v123, v217
	v_fmac_f32_e32 v8, v123, v218
	v_fmac_f32_e32 v9, v123, v219
	v_fmac_f32_e32 v6, v124, v217
	v_fmac_f32_e32 v7, v124, v218
	v_fmac_f32_e32 v8, v124, v219
	v_fmac_f32_e32 v9, v124, v220
	v_fmac_f32_e32 v6, v125, v218
	v_fmac_f32_e32 v7, v125, v219
	v_fmac_f32_e32 v8, v125, v220
	v_fmac_f32_e32 v9, v125, v221
	v_fmac_f32_e32 v6, v126, v219
	v_fmac_f32_e32 v7, v126, v220
	v_fmac_f32_e32 v8, v126, v221
	v_fmac_f32_e32 v9, v126, v222
	v_fmac_f32_e32 v6, v127, v220
	v_fmac_f32_e32 v7, v127, v221
	v_fmac_f32_e32 v8, v127, v222
	v_fmac_f32_e32 v9, v127, v223
	v_fmac_f32_e32 v6, v128, v221
	v_fmac_f32_e32 v7, v128, v222
	v_fmac_f32_e32 v8, v128, v223
	v_fmac_f32_e32 v9, v128, v224
	v_fmac_f32_e32 v6, v129, v222
	v_fmac_f32_e32 v7, v129, v223
	v_fmac_f32_e32 v8, v129, v224
	v_fmac_f32_e32 v9, v129, v225
	v_fmac_f32_e32 v6, v130, v223
	v_fmac_f32_e32 v7, v130, v224
	v_fmac_f32_e32 v8, v130, v225
	v_fmac_f32_e32 v9, v130, v226
	v_fmac_f32_e32 v6, v131, v224
	v_fmac_f32_e32 v7, v131, v225
	v_fmac_f32_e32 v8, v131, v226
	v_fmac_f32_e32 v9, v131, v227
	v_fmac_f32_e32 v6, v132, v225
	v_fmac_f32_e32 v7, v132, v226
	v_fmac_f32_e32 v8, v132, v227
	v_fmac_f32_e32 v9, v132, v228
	v_fmac_f32_e32 v6, v133, v226
	v_fmac_f32_e32 v7, v133, v227
	v_fmac_f32_e32 v8, v133, v228
	v_fmac_f32_e32 v9, v133, v229
	v_fmac_f32_e32 v6, v134, v227
	v_fmac_f32_e32 v7, v134, v228
	v_fmac_f32_e32 v8, v134, v229
	v_fmac_f32_e32 v9, v134, v230
	v_fmac_f32_e32 v6, v135, v228
	v_fmac_f32_e32 v7, v135, v229
	v_fmac_f32_e32 v8, v135, v230
	v_fmac_f32_e32 v9, v135, v231
	v_fmac_f32_e32 v6, v136, v229
	v_fmac_f32_e32 v7, v136, v230
	v_fmac_f32_e32 v8, v136, v231
	v_fmac_f32_e32 v9, v136, v232
	v_fmac_f32_e32 v6, v137, v230
	v_fmac_f32_e32 v7, v137, v231
	v_fmac_f32_e32 v8, v137, v232
	v_fmac_f32_e32 v9, v137, v233
	v_fmac_f32_e32 v6, v138, v231
	v_fmac_f32_e32 v7, v138, v232
	v_fmac_f32_e32 v8, v138, v233
	v_fmac_f32_e32 v9, v138, v234
	v_fmac_f32_e32 v6, v139, v232
	v_fmac_f32_e32 v7, v139, v233
	v_fmac_f32_e32 v8, v139, v234
	v_fmac_f32_e32 v9, v139, v235
	v_fmac_f32_e32 v6, v140, v233
	v_fmac_f32_e32 v7, v140, v234
	v_fmac_f32_e32 v8, v140, v235
	v_fmac_f32_e32 v9, v140, v236
	v_fmac_f32_e32 v6, v141, v234
	v_fmac_f32_e32 v7, v141, v235
	v_fmac_f32_e32 v8, v141, v236
	v_fmac_f32_e32 v9, v141, v237
	v_fmac_f32_e32 v6, v142, v235
	v_fmac_f32_e32 v7, v142, v236
	v_fmac_f32_e32 v8, v142, v237
	v_fmac_f32_e32 v9, v142, v238
	v_fmac_f32_e32 v6, v143, v236
	v_fmac_f32_e32 v7, v143, v237
	v_fmac_f32_e32 v8, v143, v238
	v_fmac_f32_e32 v9, v143, v239
	v_fmac_f32_e32 v6, v144, v237
	v_fmac_f32_e32 v7, v144, v238
	v_fmac_f32_e32 v8, v144, v239
	v_fmac_f32_e32 v9, v144, v240
	v_fmac_f32_e32 v6, v145, v238
	v_fmac_f32_e32 v7, v145, v239
	v_fmac_f32_e32 v8, v145, v240
	v_fmac_f32_e32 v9, v145, v241
	v_fmac_f32_e32 v6, v146, v239
	v_fmac_f32_e32 v7, v146, v240
	v_fmac_f32_e32 v8, v146, v241
	v_fmac_f32_e32 v9, v146, v242
	v_fmac_f32_e32 v6, v147, v240
	v_fmac_f32_e32 v7, v147, v241
	v_fmac_f32_e32 v8, v147, v242
	v_fmac_f32_e32 v9, v147, v243
	ds_write2st64_b32 v81, v6, v7 offset0:112 offset1:116
	ds_write2st64_b32 v81, v8, v9 offset0:120 offset1:124
	s_waitcnt lgkmcnt(0)
	s_barrier
; DI void conv_item(PREF p, int l, int tile, unsigned char* ldsb) {
;     ...
;   const float4 gg = *(const float4*)(p.conv_ng + l * 256 + lane * 4);
;   const float4 bb = *(const float4*)(p.conv_nb + l * 256 + lane * 4);
;   for (int q = 0; q < 8; ++q) {
;     int tt = w * 8 + q;
;     float4 v = *(const float4*)(Gs + tt * 256 + lane * 4);
;     float mu = wsum(v.x + v.y + v.z + v.w) * (1.f / 256.f);
;     float d0 = v.x - mu, d1 = v.y - mu, d2 = v.z - mu, d3 = v.w - mu;
;     float var = wsum(d0 * d0 + d1 * d1 + d2 * d2 + d3 * d3) * (1.f / 256.f);
	ds_read_b128 v[182:185], v82 offset:0
	ds_read_b128 v[186:189], v82 offset:1024
	ds_read_b128 v[190:193], v82 offset:2048
	ds_read_b128 v[194:197], v82 offset:3072
	ds_read_b128 v[198:201], v82 offset:4096
	ds_read_b128 v[202:205], v82 offset:5120
	ds_read_b128 v[206:209], v82 offset:6144
	ds_read_b128 v[210:213], v82 offset:7168
	v_lshrrev_b32_e32 v0, 6, v169
	v_lshl_add_u32 v0, v0, 3, s22
	v_lshlrev_b32_e32 v0, 9, v0
	v_lshl_add_u32 v0, v172, 3, v0
	v_mov_b32_e32 v102, s20
	v_mov_b32_e32 v103, s21
	v_mov_b32_e32 v3, 0
	v_mov_b32_e32 v2, v0
	v_lshl_add_u64 v[102:103], v[102:103], 0, v[2:3]
	s_waitcnt lgkmcnt(0)
	v_add_f32_e32 v214, v182, v183
	v_add_f32_e32 v215, v186, v187
	v_add_f32_e32 v216, v190, v191
	v_add_f32_e32 v217, v194, v195
	v_add_f32_e32 v218, v198, v199
	v_add_f32_e32 v219, v202, v203
	v_add_f32_e32 v220, v206, v207
	v_add_f32_e32 v221, v210, v211
	v_add_f32_e32 v214, v214, v184
	v_add_f32_e32 v215, v215, v188
	v_add_f32_e32 v216, v216, v192
	v_add_f32_e32 v217, v217, v196
	v_add_f32_e32 v218, v218, v200
	v_add_f32_e32 v219, v219, v204
	v_add_f32_e32 v220, v220, v208
	v_add_f32_e32 v221, v221, v212
	v_add_f32_e32 v214, v214, v185
	v_add_f32_e32 v215, v215, v189
	v_add_f32_e32 v216, v216, v193
	v_add_f32_e32 v217, v217, v197
	v_add_f32_e32 v218, v218, v201
	v_add_f32_e32 v219, v219, v205
	v_add_f32_e32 v220, v220, v209
	v_add_f32_e32 v221, v221, v213
	ds_bpermute_b32 v222, v85, v214
	ds_bpermute_b32 v223, v85, v215
	ds_bpermute_b32 v224, v85, v216
	ds_bpermute_b32 v225, v85, v217
	ds_bpermute_b32 v226, v85, v218
	ds_bpermute_b32 v227, v85, v219
	ds_bpermute_b32 v228, v85, v220
	ds_bpermute_b32 v229, v85, v221
	s_waitcnt lgkmcnt(0)
	v_add_f32_e32 v214, v214, v222
	v_add_f32_e32 v215, v215, v223
	v_add_f32_e32 v216, v216, v224
	v_add_f32_e32 v217, v217, v225
	v_add_f32_e32 v218, v218, v226
	v_add_f32_e32 v219, v219, v227
	v_add_f32_e32 v220, v220, v228
	v_add_f32_e32 v221, v221, v229
	ds_bpermute_b32 v222, v86, v214
	ds_bpermute_b32 v223, v86, v215
	ds_bpermute_b32 v224, v86, v216
	ds_bpermute_b32 v225, v86, v217
	ds_bpermute_b32 v226, v86, v218
	ds_bpermute_b32 v227, v86, v219
	ds_bpermute_b32 v228, v86, v220
	ds_bpermute_b32 v229, v86, v221
	s_waitcnt lgkmcnt(0)
	v_add_f32_e32 v214, v214, v222
	v_add_f32_e32 v215, v215, v223
	v_add_f32_e32 v216, v216, v224
	v_add_f32_e32 v217, v217, v225
	v_add_f32_e32 v218, v218, v226
	v_add_f32_e32 v219, v219, v227
	v_add_f32_e32 v220, v220, v228
	v_add_f32_e32 v221, v221, v229
	ds_bpermute_b32 v222, v87, v214
	ds_bpermute_b32 v223, v87, v215
	ds_bpermute_b32 v224, v87, v216
	ds_bpermute_b32 v225, v87, v217
	ds_bpermute_b32 v226, v87, v218
	ds_bpermute_b32 v227, v87, v219
	ds_bpermute_b32 v228, v87, v220
	ds_bpermute_b32 v229, v87, v221
	s_waitcnt lgkmcnt(0)
	v_add_f32_e32 v214, v214, v222
	v_add_f32_e32 v215, v215, v223
	v_add_f32_e32 v216, v216, v224
	v_add_f32_e32 v217, v217, v225
	v_add_f32_e32 v218, v218, v226
	v_add_f32_e32 v219, v219, v227
	v_add_f32_e32 v220, v220, v228
	v_add_f32_e32 v221, v221, v229
	ds_bpermute_b32 v222, v88, v214
	ds_bpermute_b32 v223, v88, v215
	ds_bpermute_b32 v224, v88, v216
	ds_bpermute_b32 v225, v88, v217
	ds_bpermute_b32 v226, v88, v218
	ds_bpermute_b32 v227, v88, v219
	ds_bpermute_b32 v228, v88, v220
	ds_bpermute_b32 v229, v88, v221
	s_waitcnt lgkmcnt(0)
	v_add_f32_e32 v214, v214, v222
	v_add_f32_e32 v215, v215, v223
	v_add_f32_e32 v216, v216, v224
	v_add_f32_e32 v217, v217, v225
	v_add_f32_e32 v218, v218, v226
	v_add_f32_e32 v219, v219, v227
	v_add_f32_e32 v220, v220, v228
	v_add_f32_e32 v221, v221, v229
	ds_bpermute_b32 v222, v89, v214
	ds_bpermute_b32 v223, v89, v215
	ds_bpermute_b32 v224, v89, v216
	ds_bpermute_b32 v225, v89, v217
	ds_bpermute_b32 v226, v89, v218
	ds_bpermute_b32 v227, v89, v219
	ds_bpermute_b32 v228, v89, v220
	ds_bpermute_b32 v229, v89, v221
	s_waitcnt lgkmcnt(0)
	v_add_f32_e32 v214, v214, v222
	v_add_f32_e32 v215, v215, v223
	v_add_f32_e32 v216, v216, v224
	v_add_f32_e32 v217, v217, v225
	v_add_f32_e32 v218, v218, v226
	v_add_f32_e32 v219, v219, v227
	v_add_f32_e32 v220, v220, v228
	v_add_f32_e32 v221, v221, v229
	ds_bpermute_b32 v222, v90, v214
	ds_bpermute_b32 v223, v90, v215
	ds_bpermute_b32 v224, v90, v216
	ds_bpermute_b32 v225, v90, v217
	ds_bpermute_b32 v226, v90, v218
	ds_bpermute_b32 v227, v90, v219
	ds_bpermute_b32 v228, v90, v220
	ds_bpermute_b32 v229, v90, v221
	s_waitcnt lgkmcnt(0)
; DI void conv_item(PREF p, int l, int tile, unsigned char* ldsb) {
;     ...
;     float mu = wsum(v.x + v.y + v.z + v.w) * (1.f / 256.f);
;     float d0 = v.x - mu, d1 = v.y - mu, d2 = v.z - mu, d3 = v.w - mu;
;     float var = wsum(d0 * d0 + d1 * d1 + d2 * d2 + d3 * d3) * (1.f / 256.f);
	v_add_f32_e32 v214, v214, v222
	v_add_f32_e32 v215, v215, v223
	v_add_f32_e32 v216, v216, v224
	v_add_f32_e32 v217, v217, v225
	v_add_f32_e32 v218, v218, v226
	v_add_f32_e32 v219, v219, v227
	v_add_f32_e32 v220, v220, v228
	v_add_f32_e32 v221, v221, v229
	v_mov_b32_e32 v0, 0x3b800000
	v_mul_f32_e32 v230, v214, v0
	v_mul_f32_e32 v231, v215, v0
	v_mul_f32_e32 v232, v216, v0
	v_mul_f32_e32 v233, v217, v0
	v_mul_f32_e32 v234, v218, v0
	v_mul_f32_e32 v235, v219, v0
	v_mul_f32_e32 v236, v220, v0
	v_mul_f32_e32 v237, v221, v0
	v_sub_f32_e32 v182, v182, v230
	v_sub_f32_e32 v183, v183, v230
	v_sub_f32_e32 v184, v184, v230
	v_sub_f32_e32 v185, v185, v230
	v_sub_f32_e32 v186, v186, v231
	v_sub_f32_e32 v187, v187, v231
	v_sub_f32_e32 v188, v188, v231
	v_sub_f32_e32 v189, v189, v231
	v_sub_f32_e32 v190, v190, v232
	v_sub_f32_e32 v191, v191, v232
	v_sub_f32_e32 v192, v192, v232
	v_sub_f32_e32 v193, v193, v232
	v_sub_f32_e32 v194, v194, v233
	v_sub_f32_e32 v195, v195, v233
	v_sub_f32_e32 v196, v196, v233
	v_sub_f32_e32 v197, v197, v233
	v_sub_f32_e32 v198, v198, v234
	v_sub_f32_e32 v199, v199, v234
	v_sub_f32_e32 v200, v200, v234
	v_sub_f32_e32 v201, v201, v234
	v_sub_f32_e32 v202, v202, v235
	v_sub_f32_e32 v203, v203, v235
	v_sub_f32_e32 v204, v204, v235
	v_sub_f32_e32 v205, v205, v235
	v_sub_f32_e32 v206, v206, v236
	v_sub_f32_e32 v207, v207, v236
	v_sub_f32_e32 v208, v208, v236
	v_sub_f32_e32 v209, v209, v236
	v_sub_f32_e32 v210, v210, v237
	v_sub_f32_e32 v211, v211, v237
	v_sub_f32_e32 v212, v212, v237
	v_sub_f32_e32 v213, v213, v237
	v_mul_f32_e32 v214, v182, v182
	v_mul_f32_e32 v215, v186, v186
	v_mul_f32_e32 v216, v190, v190
	v_mul_f32_e32 v217, v194, v194
	v_mul_f32_e32 v218, v198, v198
	v_mul_f32_e32 v219, v202, v202
	v_mul_f32_e32 v220, v206, v206
	v_mul_f32_e32 v221, v210, v210
	v_fmac_f32_e32 v214, v183, v183
	v_fmac_f32_e32 v215, v187, v187
	v_fmac_f32_e32 v216, v191, v191
	v_fmac_f32_e32 v217, v195, v195
	v_fmac_f32_e32 v218, v199, v199
	v_fmac_f32_e32 v219, v203, v203
	v_fmac_f32_e32 v220, v207, v207
	v_fmac_f32_e32 v221, v211, v211
	v_fmac_f32_e32 v214, v184, v184
	v_fmac_f32_e32 v215, v188, v188
	v_fmac_f32_e32 v216, v192, v192
	v_fmac_f32_e32 v217, v196, v196
	v_fmac_f32_e32 v218, v200, v200
	v_fmac_f32_e32 v219, v204, v204
	v_fmac_f32_e32 v220, v208, v208
	v_fmac_f32_e32 v221, v212, v212
	v_fmac_f32_e32 v214, v185, v185
	v_fmac_f32_e32 v215, v189, v189
	v_fmac_f32_e32 v216, v193, v193
	v_fmac_f32_e32 v217, v197, v197
	v_fmac_f32_e32 v218, v201, v201
	v_fmac_f32_e32 v219, v205, v205
	v_fmac_f32_e32 v220, v209, v209
	v_fmac_f32_e32 v221, v213, v213
	ds_bpermute_b32 v222, v85, v214
	ds_bpermute_b32 v223, v85, v215
	ds_bpermute_b32 v224, v85, v216
	ds_bpermute_b32 v225, v85, v217
	ds_bpermute_b32 v226, v85, v218
	ds_bpermute_b32 v227, v85, v219
	ds_bpermute_b32 v228, v85, v220
	ds_bpermute_b32 v229, v85, v221
	s_waitcnt lgkmcnt(0)
	v_add_f32_e32 v214, v214, v222
	v_add_f32_e32 v215, v215, v223
	v_add_f32_e32 v216, v216, v224
	v_add_f32_e32 v217, v217, v225
	v_add_f32_e32 v218, v218, v226
	v_add_f32_e32 v219, v219, v227
	v_add_f32_e32 v220, v220, v228
	v_add_f32_e32 v221, v221, v229
	ds_bpermute_b32 v222, v86, v214
	ds_bpermute_b32 v223, v86, v215
	ds_bpermute_b32 v224, v86, v216
	ds_bpermute_b32 v225, v86, v217
	ds_bpermute_b32 v226, v86, v218
	ds_bpermute_b32 v227, v86, v219
	ds_bpermute_b32 v228, v86, v220
	ds_bpermute_b32 v229, v86, v221
	s_waitcnt lgkmcnt(0)
	v_add_f32_e32 v214, v214, v222
	v_add_f32_e32 v215, v215, v223
	v_add_f32_e32 v216, v216, v224
	v_add_f32_e32 v217, v217, v225
	v_add_f32_e32 v218, v218, v226
	v_add_f32_e32 v219, v219, v227
	v_add_f32_e32 v220, v220, v228
	v_add_f32_e32 v221, v221, v229
	ds_bpermute_b32 v222, v87, v214
	ds_bpermute_b32 v223, v87, v215
	ds_bpermute_b32 v224, v87, v216
	ds_bpermute_b32 v225, v87, v217
	ds_bpermute_b32 v226, v87, v218
	ds_bpermute_b32 v227, v87, v219
	ds_bpermute_b32 v228, v87, v220
	ds_bpermute_b32 v229, v87, v221
	s_waitcnt lgkmcnt(0)
	v_add_f32_e32 v214, v214, v222
	v_add_f32_e32 v215, v215, v223
	v_add_f32_e32 v216, v216, v224
	v_add_f32_e32 v217, v217, v225
	v_add_f32_e32 v218, v218, v226
	v_add_f32_e32 v219, v219, v227
	v_add_f32_e32 v220, v220, v228
	v_add_f32_e32 v221, v221, v229
	ds_bpermute_b32 v222, v88, v214
	ds_bpermute_b32 v223, v88, v215
	ds_bpermute_b32 v224, v88, v216
	ds_bpermute_b32 v225, v88, v217
	ds_bpermute_b32 v226, v88, v218
	ds_bpermute_b32 v227, v88, v219
	ds_bpermute_b32 v228, v88, v220
	ds_bpermute_b32 v229, v88, v221
	s_waitcnt lgkmcnt(0)
	v_add_f32_e32 v214, v214, v222
	v_add_f32_e32 v215, v215, v223
	v_add_f32_e32 v216, v216, v224
	v_add_f32_e32 v217, v217, v225
	v_add_f32_e32 v218, v218, v226
	v_add_f32_e32 v219, v219, v227
	v_add_f32_e32 v220, v220, v228
	v_add_f32_e32 v221, v221, v229
	ds_bpermute_b32 v222, v89, v214
	ds_bpermute_b32 v223, v89, v215
	ds_bpermute_b32 v224, v89, v216
	ds_bpermute_b32 v225, v89, v217
	ds_bpermute_b32 v226, v89, v218
	ds_bpermute_b32 v227, v89, v219
	ds_bpermute_b32 v228, v89, v220
	ds_bpermute_b32 v229, v89, v221
	s_waitcnt lgkmcnt(0)
	v_add_f32_e32 v214, v214, v222
	v_add_f32_e32 v215, v215, v223
	v_add_f32_e32 v216, v216, v224
	v_add_f32_e32 v217, v217, v225
	v_add_f32_e32 v218, v218, v226
	v_add_f32_e32 v219, v219, v227
	v_add_f32_e32 v220, v220, v228
	v_add_f32_e32 v221, v221, v229
	ds_bpermute_b32 v222, v90, v214
	ds_bpermute_b32 v223, v90, v215
	ds_bpermute_b32 v224, v90, v216
	ds_bpermute_b32 v225, v90, v217
	ds_bpermute_b32 v226, v90, v218
	ds_bpermute_b32 v227, v90, v219
	ds_bpermute_b32 v228, v90, v220
	ds_bpermute_b32 v229, v90, v221
	s_waitcnt lgkmcnt(0)
; DI float silu(float x) { return x / (1.f + __expf(-x)); }
; DI void conv_item(PREF p, int l, int tile, unsigned char* ldsb) {
;     ...
;     float var = wsum(d0 * d0 + d1 * d1 + d2 * d2 + d3 * d3) * (1.f / 256.f);
;     float rs = rsqrtf(var + 1e-5f);
;     float y0 = silu(d0 * rs * gg.x + bb.x), y1 = silu(d1 * rs * gg.y + bb.y);
;     float y2 = silu(d2 * rs * gg.z + bb.z), y3 = silu(d3 * rs * gg.w + bb.w);
	v_add_f32_e32 v214, v214, v222
	v_add_f32_e32 v215, v215, v223
	v_add_f32_e32 v216, v216, v224
	v_add_f32_e32 v217, v217, v225
	v_add_f32_e32 v218, v218, v226
	v_add_f32_e32 v219, v219, v227
	v_add_f32_e32 v220, v220, v228
	v_add_f32_e32 v221, v221, v229
	v_mov_b32_e32 v2, 0x3727c5ac
	v_fma_f32 v230, v214, v0, v2
	v_fma_f32 v231, v215, v0, v2
	v_fma_f32 v232, v216, v0, v2
	v_fma_f32 v233, v217, v0, v2
	v_fma_f32 v234, v218, v0, v2
	v_fma_f32 v235, v219, v0, v2
	v_fma_f32 v236, v220, v0, v2
	v_fma_f32 v237, v221, v0, v2
	v_rsq_f32_e32 v230, v230
	v_rsq_f32_e32 v231, v231
	v_rsq_f32_e32 v232, v232
	v_rsq_f32_e32 v233, v233
	v_rsq_f32_e32 v234, v234
	v_rsq_f32_e32 v235, v235
	v_rsq_f32_e32 v236, v236
	v_rsq_f32_e32 v237, v237
	v_mul_f32_e32 v182, v182, v230
	v_mul_f32_e32 v183, v183, v230
	v_mul_f32_e32 v184, v184, v230
	v_mul_f32_e32 v185, v185, v230
	v_mul_f32_e32 v186, v186, v231
	v_mul_f32_e32 v187, v187, v231
	v_mul_f32_e32 v188, v188, v231
	v_mul_f32_e32 v189, v189, v231
	v_mul_f32_e32 v190, v190, v232
	v_mul_f32_e32 v191, v191, v232
	v_mul_f32_e32 v192, v192, v232
	v_mul_f32_e32 v193, v193, v232
	v_mul_f32_e32 v194, v194, v233
	v_mul_f32_e32 v195, v195, v233
	v_mul_f32_e32 v196, v196, v233
	v_mul_f32_e32 v197, v197, v233
	v_mul_f32_e32 v198, v198, v234
	v_mul_f32_e32 v199, v199, v234
	v_mul_f32_e32 v200, v200, v234
	v_mul_f32_e32 v201, v201, v234
	v_mul_f32_e32 v202, v202, v235
	v_mul_f32_e32 v203, v203, v235
	v_mul_f32_e32 v204, v204, v235
	v_mul_f32_e32 v205, v205, v235
	v_mul_f32_e32 v206, v206, v236
	v_mul_f32_e32 v207, v207, v236
	v_mul_f32_e32 v208, v208, v236
	v_mul_f32_e32 v209, v209, v236
	v_mul_f32_e32 v210, v210, v237
	v_mul_f32_e32 v211, v211, v237
	v_mul_f32_e32 v212, v212, v237
	v_mul_f32_e32 v213, v213, v237
	v_fma_f32 v182, v182, v92, v96
	v_fma_f32 v183, v183, v93, v97
	v_fma_f32 v184, v184, v94, v98
	v_fma_f32 v185, v185, v95, v99
	v_fma_f32 v186, v186, v92, v96
	v_fma_f32 v187, v187, v93, v97
	v_fma_f32 v188, v188, v94, v98
	v_fma_f32 v189, v189, v95, v99
	v_fma_f32 v190, v190, v92, v96
	v_fma_f32 v191, v191, v93, v97
	v_fma_f32 v192, v192, v94, v98
	v_fma_f32 v193, v193, v95, v99
	v_fma_f32 v194, v194, v92, v96
	v_fma_f32 v195, v195, v93, v97
	v_fma_f32 v196, v196, v94, v98
	v_fma_f32 v197, v197, v95, v99
	v_fma_f32 v198, v198, v92, v96
	v_fma_f32 v199, v199, v93, v97
	v_fma_f32 v200, v200, v94, v98
	v_fma_f32 v201, v201, v95, v99
	v_fma_f32 v202, v202, v92, v96
	v_fma_f32 v203, v203, v93, v97
	v_fma_f32 v204, v204, v94, v98
	v_fma_f32 v205, v205, v95, v99
	v_fma_f32 v206, v206, v92, v96
	v_fma_f32 v207, v207, v93, v97
	v_fma_f32 v208, v208, v94, v98
	v_fma_f32 v209, v209, v95, v99
	v_fma_f32 v210, v210, v92, v96
	v_fma_f32 v211, v211, v93, v97
	v_fma_f32 v212, v212, v94, v98
	v_fma_f32 v213, v213, v95, v99
	v_mul_f32_e32 v2, 0xbfb8aa3b, v182
	v_mul_f32_e32 v3, 0xbfb8aa3b, v183
	v_mul_f32_e32 v4, 0xbfb8aa3b, v184
	v_mul_f32_e32 v5, 0xbfb8aa3b, v185
	v_mul_f32_e32 v6, 0xbfb8aa3b, v186
	v_mul_f32_e32 v7, 0xbfb8aa3b, v187
	v_mul_f32_e32 v8, 0xbfb8aa3b, v188
	v_mul_f32_e32 v9, 0xbfb8aa3b, v189
	v_mul_f32_e32 v10, 0xbfb8aa3b, v190
	v_mul_f32_e32 v11, 0xbfb8aa3b, v191
	v_mul_f32_e32 v12, 0xbfb8aa3b, v192
	v_mul_f32_e32 v13, 0xbfb8aa3b, v193
	v_mul_f32_e32 v14, 0xbfb8aa3b, v194
	v_mul_f32_e32 v15, 0xbfb8aa3b, v195
	v_mul_f32_e32 v16, 0xbfb8aa3b, v196
	v_mul_f32_e32 v17, 0xbfb8aa3b, v197
	v_mul_f32_e32 v18, 0xbfb8aa3b, v198
	v_mul_f32_e32 v19, 0xbfb8aa3b, v199
	v_mul_f32_e32 v20, 0xbfb8aa3b, v200
	v_mul_f32_e32 v21, 0xbfb8aa3b, v201
	v_mul_f32_e32 v22, 0xbfb8aa3b, v202
	v_mul_f32_e32 v23, 0xbfb8aa3b, v203
	v_mul_f32_e32 v24, 0xbfb8aa3b, v204
	v_mul_f32_e32 v25, 0xbfb8aa3b, v205
	v_mul_f32_e32 v26, 0xbfb8aa3b, v206
	v_mul_f32_e32 v27, 0xbfb8aa3b, v207
	v_mul_f32_e32 v28, 0xbfb8aa3b, v208
	v_mul_f32_e32 v29, 0xbfb8aa3b, v209
	v_mul_f32_e32 v30, 0xbfb8aa3b, v210
	v_mul_f32_e32 v31, 0xbfb8aa3b, v211
	v_mul_f32_e32 v32, 0xbfb8aa3b, v212
	v_mul_f32_e32 v33, 0xbfb8aa3b, v213
	v_exp_f32_e32 v2, v2
	v_exp_f32_e32 v3, v3
	v_exp_f32_e32 v4, v4
	v_exp_f32_e32 v5, v5
	v_exp_f32_e32 v6, v6
	v_exp_f32_e32 v7, v7
	v_exp_f32_e32 v8, v8
	v_exp_f32_e32 v9, v9
	v_exp_f32_e32 v10, v10
	v_exp_f32_e32 v11, v11
	v_exp_f32_e32 v12, v12
	v_exp_f32_e32 v13, v13
; DI int vbid() { return (int)blockIdx.x * 2 + half_(); }
; DI int vgrid() { return (int)gridDim.x * 2; }
; DI unsigned pack2(float a, float b) { unsigned r; asm("v_cvt_pk_bf16_f32 %0, %1, %2\n\ts_nop 1" : "=v"(r) : "v"(a), "v"(b)); return r; }
; DI float silu(float x) { return x / (1.f + __expf(-x)); }
; DI void conv_item(PREF p, int l, int tile, unsigned char* ldsb) {
;     ...
;     float y0 = silu(d0 * rs * gg.x + bb.x), y1 = silu(d1 * rs * gg.y + bb.y);
;     float y2 = silu(d2 * rs * gg.z + bb.z), y3 = silu(d3 * rs * gg.w + bb.w);
;     u32x2 ov; ov.x = pack2(y0, y1); ov.y = pack2(y2, y3);
;     *(u32x2*)(p.cA + (size_t)(t0 + tt) * 256 + lane * 4) = ov;
; DI void phase_mix1(PREF p, int l, unsigned char* ldsb) {
;     ...
;   for (int it = vbid(); it < 1024; it += vgrid()) conv_item(p, l, it, ldsb);
	v_exp_f32_e32 v14, v14
	v_exp_f32_e32 v15, v15
	v_exp_f32_e32 v16, v16
	v_exp_f32_e32 v17, v17
	v_exp_f32_e32 v18, v18
	v_exp_f32_e32 v19, v19
	v_exp_f32_e32 v20, v20
	v_exp_f32_e32 v21, v21
	v_exp_f32_e32 v22, v22
	v_exp_f32_e32 v23, v23
	v_exp_f32_e32 v24, v24
	v_exp_f32_e32 v25, v25
	v_exp_f32_e32 v26, v26
	v_exp_f32_e32 v27, v27
	v_exp_f32_e32 v28, v28
	v_exp_f32_e32 v29, v29
	v_exp_f32_e32 v30, v30
	v_exp_f32_e32 v31, v31
	v_exp_f32_e32 v32, v32
	v_exp_f32_e32 v33, v33
	v_add_f32_e32 v2, 1.0, v2
	v_add_f32_e32 v3, 1.0, v3
	v_add_f32_e32 v4, 1.0, v4
	v_add_f32_e32 v5, 1.0, v5
	v_add_f32_e32 v6, 1.0, v6
	v_add_f32_e32 v7, 1.0, v7
	v_add_f32_e32 v8, 1.0, v8
	v_add_f32_e32 v9, 1.0, v9
	v_add_f32_e32 v10, 1.0, v10
	v_add_f32_e32 v11, 1.0, v11
	v_add_f32_e32 v12, 1.0, v12
	v_add_f32_e32 v13, 1.0, v13
	v_add_f32_e32 v14, 1.0, v14
	v_add_f32_e32 v15, 1.0, v15
	v_add_f32_e32 v16, 1.0, v16
	v_add_f32_e32 v17, 1.0, v17
	v_add_f32_e32 v18, 1.0, v18
	v_add_f32_e32 v19, 1.0, v19
	v_add_f32_e32 v20, 1.0, v20
	v_add_f32_e32 v21, 1.0, v21
	v_add_f32_e32 v22, 1.0, v22
	v_add_f32_e32 v23, 1.0, v23
	v_add_f32_e32 v24, 1.0, v24
	v_add_f32_e32 v25, 1.0, v25
	v_add_f32_e32 v26, 1.0, v26
	v_add_f32_e32 v27, 1.0, v27
	v_add_f32_e32 v28, 1.0, v28
	v_add_f32_e32 v29, 1.0, v29
	v_add_f32_e32 v30, 1.0, v30
	v_add_f32_e32 v31, 1.0, v31
	v_add_f32_e32 v32, 1.0, v32
	v_add_f32_e32 v33, 1.0, v33
	v_rcp_f32_e32 v2, v2
	v_rcp_f32_e32 v3, v3
	v_rcp_f32_e32 v4, v4
	v_rcp_f32_e32 v5, v5
	v_rcp_f32_e32 v6, v6
	v_rcp_f32_e32 v7, v7
	v_rcp_f32_e32 v8, v8
	v_rcp_f32_e32 v9, v9
	v_rcp_f32_e32 v10, v10
	v_rcp_f32_e32 v11, v11
	v_rcp_f32_e32 v12, v12
	v_rcp_f32_e32 v13, v13
	v_rcp_f32_e32 v14, v14
	v_rcp_f32_e32 v15, v15
	v_rcp_f32_e32 v16, v16
	v_rcp_f32_e32 v17, v17
	v_rcp_f32_e32 v18, v18
	v_rcp_f32_e32 v19, v19
	v_rcp_f32_e32 v20, v20
	v_rcp_f32_e32 v21, v21
	v_rcp_f32_e32 v22, v22
	v_rcp_f32_e32 v23, v23
	v_rcp_f32_e32 v24, v24
	v_rcp_f32_e32 v25, v25
	v_rcp_f32_e32 v26, v26
	v_rcp_f32_e32 v27, v27
	v_rcp_f32_e32 v28, v28
	v_rcp_f32_e32 v29, v29
	v_rcp_f32_e32 v30, v30
	v_rcp_f32_e32 v31, v31
	v_rcp_f32_e32 v32, v32
	v_rcp_f32_e32 v33, v33
	v_mul_f32_e32 v182, v182, v2
	v_mul_f32_e32 v183, v183, v3
	v_mul_f32_e32 v184, v184, v4
	v_mul_f32_e32 v185, v185, v5
	v_mul_f32_e32 v186, v186, v6
	v_mul_f32_e32 v187, v187, v7
	v_mul_f32_e32 v188, v188, v8
	v_mul_f32_e32 v189, v189, v9
	v_mul_f32_e32 v190, v190, v10
	v_mul_f32_e32 v191, v191, v11
	v_mul_f32_e32 v192, v192, v12
	v_mul_f32_e32 v193, v193, v13
	v_mul_f32_e32 v194, v194, v14
	v_mul_f32_e32 v195, v195, v15
	v_mul_f32_e32 v196, v196, v16
	v_mul_f32_e32 v197, v197, v17
	v_mul_f32_e32 v198, v198, v18
	v_mul_f32_e32 v199, v199, v19
	v_mul_f32_e32 v200, v200, v20
	v_mul_f32_e32 v201, v201, v21
	v_mul_f32_e32 v202, v202, v22
	v_mul_f32_e32 v203, v203, v23
	v_mul_f32_e32 v204, v204, v24
	v_mul_f32_e32 v205, v205, v25
	v_mul_f32_e32 v206, v206, v26
	v_mul_f32_e32 v207, v207, v27
	v_mul_f32_e32 v208, v208, v28
	v_mul_f32_e32 v209, v209, v29
	v_mul_f32_e32 v210, v210, v30
	v_mul_f32_e32 v211, v211, v31
	v_mul_f32_e32 v212, v212, v32
	v_mul_f32_e32 v213, v213, v33
	v_cvt_pk_bf16_f32 v2, v182, v183
	v_cvt_pk_bf16_f32 v3, v184, v185
	v_cvt_pk_bf16_f32 v4, v186, v187
	v_cvt_pk_bf16_f32 v5, v188, v189
	v_cvt_pk_bf16_f32 v6, v190, v191
	v_cvt_pk_bf16_f32 v7, v192, v193
	v_cvt_pk_bf16_f32 v8, v194, v195
	v_cvt_pk_bf16_f32 v9, v196, v197
	v_cvt_pk_bf16_f32 v10, v198, v199
	v_cvt_pk_bf16_f32 v11, v200, v201
	v_cvt_pk_bf16_f32 v12, v202, v203
	v_cvt_pk_bf16_f32 v13, v204, v205
	v_cvt_pk_bf16_f32 v14, v206, v207
	v_cvt_pk_bf16_f32 v15, v208, v209
	v_cvt_pk_bf16_f32 v16, v210, v211
	v_cvt_pk_bf16_f32 v17, v212, v213
	global_store_dwordx2 v[102:103], v[2:3], off
	global_store_dwordx2 v[102:103], v[4:5], off offset:512
	global_store_dwordx2 v[102:103], v[6:7], off offset:1024
	global_store_dwordx2 v[102:103], v[8:9], off offset:1536
	global_store_dwordx2 v[102:103], v[10:11], off offset:2048
	global_store_dwordx2 v[102:103], v[12:13], off offset:2560
	global_store_dwordx2 v[102:103], v[14:15], off offset:3072
	global_store_dwordx2 v[102:103], v[16:17], off offset:3584
	s_add_i32 s28, s28, s71
	s_cmpk_gt_i32 s28, 0x3ff
	s_cbranch_scc0 .Lmy_conv_item
